# v30 with all s_setprio in the four GEMM K-loops replaced by s_nop 0 (power-bound loop: priority flips only cost)
# speedup vs baseline: 1.0028x; 1.0028x over previous
; #define PG8_STAGE(bufoff, gbase, voff) do { _Pragma("unroll") for (int _i = 0; _i < 2; ++_i) \
;         __builtin_amdgcn_global_load_lds((const unsigned*)((const char*)(gbase) + (voff)[_i]), (PG8_LAS unsigned*)(lds + (bufoff) + ldsw + _i * 8192), 16, 0, 0); } while (0)
; #define PG8_LDA(dst, b, h) do { _Pragma("unroll") for (int m = 0; m < 4; ++m) _Pragma("unroll") for (int k = 0; k < 2; ++k) dst[m][k] = *(const PG8_LAS bf16x8*)(lds + PG8_SA(b, h) + aoff + m * 2048 + k * 1024); } while (0)
; #define PG8_LDB(dst, b, h) do { _Pragma("unroll") for (int n = 0; n < 2; ++n) _Pragma("unroll") for (int k = 0; k < 2; ++k) dst[n][k] = *(const PG8_LAS bf16x8*)(lds + PG8_SB(b, h) + boff + n * 2048 + k * 1024); } while (0)
; #define PG8_MMA(ai, bj, At, Bt) do { __builtin_amdgcn_s_setprio(1); _Pragma("unroll") for (int m = 0; m < 4; ++m) _Pragma("unroll") for (int n = 0; n < 2; ++n) _Pragma("unroll") for (int k = 0; k < 2; ++k) \
;         acc[ai][bj][m][n] = __builtin_amdgcn_mfma_f32_16x16x32_bf16(Bt[n][k], At[m][k], acc[ai][bj][m][n], 0, 0, 0); __builtin_amdgcn_s_setprio(0); } while (0)
; #define PG8_WAIT_V(n) asm volatile("s_waitcnt vmcnt(" #n ")" ::: "memory")
; #define PG8_WAIT_L(n) asm volatile("s_waitcnt lgkmcnt(" #n ")" ::: "memory")
; #define PG8_BAR __builtin_amdgcn_s_barrier()
; #define PG8_SCHED __builtin_amdgcn_sched_barrier(0)
; template <class Epi, class Sched, bool ALIGN_EPI = false, bool SP2 = false>
; __device__ __forceinline__ void gemm_phase(PG8_LAS unsigned char* lds, const Gemm g, const Sched& S, const Epi& E, const int wave_s) {
;     ...
;             PG8_LDB(B0, 0, 0); PG8_LDB(B1, 0, 1); PG8_SCHED; PG8_LDA(At, 0, 0); PG8_STAGE(PG8_SA(1, 1), a1 + hstep, voffA);
;             PG8_WAIT_V(8); PG8_WAIT_L(0); PG8_BAR; PG8_MMA(0, 0, At, B0); PG8_MMA(0, 1, At, B1); PG8_BAR; PG8_SCHED;
;             PG8_LDA(At, 0, 1); PG8_STAGE(PG8_SB(0, 0), b2, voffB); PG8_STAGE(PG8_SB(0, 1), b2 + bhstep, voffB); PG8_STAGE(PG8_SA(0, 0), a2, voffA);
;             PG8_WAIT_V(8); PG8_WAIT_L(0); PG8_BAR; PG8_MMA(1, 0, At, B0); PG8_MMA(1, 1, At, B1); PG8_BAR; PG8_SCHED;
.LBB0_136:
	s_add_u32 s42, s20, 0xfffc0080
	s_addc_u32 s43, s21, -1
	s_add_i32 s71, 0, 0x10000
	s_cmp_eq_u32 s70, 12
	s_cselect_b32 s45, s65, s43
	s_cselect_b32 s44, s66, s42
	v_add_u32_e32 v0, s71, v171
	s_cselect_b32 s43, s53, s69
	s_cselect_b32 s42, s67, s68
	s_add_i32 s74, 0, 0x14000
	ds_read_b128 v[146:149], v0
	ds_read_b128 v[150:153], v0 offset:1024
	ds_read_b128 v[154:157], v0 offset:2048
	ds_read_b128 v[158:161], v0 offset:3072
	v_add_u32_e32 v0, s74, v171
	ds_read_b128 v[162:165], v0
	ds_read_b128 v[166:169], v0 offset:1024
	s_nop 0
	ds_read_b128 v[182:185], v0 offset:2048
	ds_read_b128 v[186:189], v0 offset:3072
	v_lshl_add_u64 v[224:225], s[20:21], 0, v[142:143]
	s_add_i32 m0, s7, 0xc000
	ds_read_b128 v[190:193], v177
	ds_read_b128 v[194:197], v177 offset:1024
	ds_read_b128 v[198:201], v177 offset:2048
	ds_read_b128 v[204:207], v177 offset:3072
	ds_read_b128 v[208:211], v177 offset:4096
	ds_read_b128 v[212:215], v177 offset:5120
	ds_read_b128 v[216:219], v177 offset:6144
	ds_read_b128 v[220:223], v177 offset:7168
	global_load_lds_dwordx4 v[224:225], off
	v_lshl_add_u64 v[224:225], s[20:21], 0, v[144:145]
	s_add_i32 m0, s7, 0xe000
	s_nop 0
	global_load_lds_dwordx4 v[224:225], off
	s_waitcnt vmcnt(8)
	s_waitcnt lgkmcnt(0)
	s_barrier
	s_nop 0
	s_waitcnt lgkmcnt(0)
	v_mfma_f32_16x16x32_bf16 v[126:129], v[146:149], v[190:193], v[126:129]
	v_mfma_f32_16x16x32_bf16 v[126:129], v[150:153], v[194:197], v[126:129]
	v_mfma_f32_16x16x32_bf16 v[122:125], v[154:157], v[190:193], v[122:125]
	v_mfma_f32_16x16x32_bf16 v[122:125], v[158:161], v[194:197], v[122:125]
	v_mfma_f32_16x16x32_bf16 v[110:113], v[146:149], v[198:201], v[110:113]
	v_mfma_f32_16x16x32_bf16 v[110:113], v[150:153], v[204:207], v[110:113]
	v_mfma_f32_16x16x32_bf16 v[106:109], v[154:157], v[198:201], v[106:109]
	v_mfma_f32_16x16x32_bf16 v[106:109], v[158:161], v[204:207], v[106:109]
	v_mfma_f32_16x16x32_bf16 v[94:97], v[146:149], v[208:211], v[94:97]
	v_mfma_f32_16x16x32_bf16 v[94:97], v[150:153], v[212:215], v[94:97]
	v_mfma_f32_16x16x32_bf16 v[90:93], v[154:157], v[208:211], v[90:93]
	v_mfma_f32_16x16x32_bf16 v[90:93], v[158:161], v[212:215], v[90:93]
	v_mfma_f32_16x16x32_bf16 v[78:81], v[146:149], v[216:219], v[78:81]
	v_mfma_f32_16x16x32_bf16 v[78:81], v[150:153], v[220:223], v[78:81]
	v_mfma_f32_16x16x32_bf16 v[74:77], v[154:157], v[216:219], v[74:77]
	v_mfma_f32_16x16x32_bf16 v[74:77], v[158:161], v[220:223], v[74:77]
	s_nop 0
	s_nop 0
	v_mfma_f32_16x16x32_bf16 v[118:121], v[162:165], v[190:193], v[118:121]
	v_mfma_f32_16x16x32_bf16 v[118:121], v[166:169], v[194:197], v[118:121]
	v_mfma_f32_16x16x32_bf16 v[114:117], v[182:185], v[190:193], v[114:117]
	v_mfma_f32_16x16x32_bf16 v[114:117], v[186:189], v[194:197], v[114:117]
	v_mfma_f32_16x16x32_bf16 v[102:105], v[162:165], v[198:201], v[102:105]
	v_mfma_f32_16x16x32_bf16 v[102:105], v[166:169], v[204:207], v[102:105]
	v_mfma_f32_16x16x32_bf16 v[98:101], v[182:185], v[198:201], v[98:101]
	v_mfma_f32_16x16x32_bf16 v[98:101], v[186:189], v[204:207], v[98:101]
	v_mfma_f32_16x16x32_bf16 v[86:89], v[162:165], v[208:211], v[86:89]
	v_mfma_f32_16x16x32_bf16 v[86:89], v[166:169], v[212:215], v[86:89]
	v_mfma_f32_16x16x32_bf16 v[82:85], v[182:185], v[208:211], v[82:85]
	v_mfma_f32_16x16x32_bf16 v[82:85], v[186:189], v[212:215], v[82:85]
	v_mfma_f32_16x16x32_bf16 v[70:73], v[162:165], v[216:219], v[70:73]
	v_mfma_f32_16x16x32_bf16 v[70:73], v[166:169], v[220:223], v[70:73]
	v_mfma_f32_16x16x32_bf16 v[66:69], v[182:185], v[216:219], v[66:69]
	v_mfma_f32_16x16x32_bf16 v[66:69], v[186:189], v[220:223], v[66:69]
	s_nop 0
	s_barrier
	s_add_i32 s71, s71, s6
	v_lshl_add_u64 v[224:225], s[42:43], 0, v[134:135]
	s_mov_b32 m0, s71
	ds_read_b128 v[190:193], v177 offset:16384
	ds_read_b128 v[194:197], v177 offset:17408
	ds_read_b128 v[198:201], v177 offset:18432
	ds_read_b128 v[204:207], v177 offset:19456
	ds_read_b128 v[208:211], v177 offset:20480
	ds_read_b128 v[212:215], v177 offset:21504
	ds_read_b128 v[216:219], v177 offset:22528
	ds_read_b128 v[220:223], v177 offset:23552
	global_load_lds_dwordx4 v[224:225], off
	s_add_i32 m0, s71, 0x2000
	s_add_u32 s84, s42, 0x10000
	v_lshl_add_u64 v[226:227], s[42:43], 0, v[138:139]
	s_addc_u32 s85, s43, 0
	s_add_i32 s71, s74, s6
	global_load_lds_dwordx4 v[226:227], off
	v_lshl_add_u64 v[228:229], s[84:85], 0, v[134:135]
	s_mov_b32 m0, s71
	v_lshl_add_u64 v[230:231], s[44:45], 0, v[136:137]
	global_load_lds_dwordx4 v[228:229], off
	v_lshl_add_u64 v[228:229], s[84:85], 0, v[138:139]
	s_add_i32 m0, s71, 0x2000
	s_nop 0
	global_load_lds_dwordx4 v[228:229], off
	v_lshl_add_u64 v[228:229], s[44:45], 0, v[132:133]
	s_mov_b32 m0, s7
	s_nop 0
	global_load_lds_dwordx4 v[228:229], off
	s_mov_b32 m0, s57
	s_nop 0
	global_load_lds_dwordx4 v[230:231], off
	s_waitcnt vmcnt(8)
	s_waitcnt lgkmcnt(0)
	s_barrier
; #define PG8_STAGE(bufoff, gbase, voff) do { _Pragma("unroll") for (int _i = 0; _i < 2; ++_i) \
;         __builtin_amdgcn_global_load_lds((const unsigned*)((const char*)(gbase) + (voff)[_i]), (PG8_LAS unsigned*)(lds + (bufoff) + ldsw + _i * 8192), 16, 0, 0); } while (0)
; #define PG8_LDA(dst, b, h) do { _Pragma("unroll") for (int m = 0; m < 4; ++m) _Pragma("unroll") for (int k = 0; k < 2; ++k) dst[m][k] = *(const PG8_LAS bf16x8*)(lds + PG8_SA(b, h) + aoff + m * 2048 + k * 1024); } while (0)
; #define PG8_LDB(dst, b, h) do { _Pragma("unroll") for (int n = 0; n < 2; ++n) _Pragma("unroll") for (int k = 0; k < 2; ++k) dst[n][k] = *(const PG8_LAS bf16x8*)(lds + PG8_SB(b, h) + boff + n * 2048 + k * 1024); } while (0)
; #define PG8_MMA(ai, bj, At, Bt) do { __builtin_amdgcn_s_setprio(1); _Pragma("unroll") for (int m = 0; m < 4; ++m) _Pragma("unroll") for (int n = 0; n < 2; ++n) _Pragma("unroll") for (int k = 0; k < 2; ++k) \
;         acc[ai][bj][m][n] = __builtin_amdgcn_mfma_f32_16x16x32_bf16(Bt[n][k], At[m][k], acc[ai][bj][m][n], 0, 0, 0); __builtin_amdgcn_s_setprio(0); } while (0)
; #define PG8_WAIT_V(n) asm volatile("s_waitcnt vmcnt(" #n ")" ::: "memory")
; #define PG8_WAIT_L(n) asm volatile("s_waitcnt lgkmcnt(" #n ")" ::: "memory")
; #define PG8_BAR __builtin_amdgcn_s_barrier()
; #define PG8_SCHED __builtin_amdgcn_sched_barrier(0)
; template <class Epi, class Sched, bool ALIGN_EPI = false, bool SP2 = false>
; __device__ __forceinline__ void gemm_phase(PG8_LAS unsigned char* lds, const Gemm g, const Sched& S, const Epi& E, const int wave_s) {
;     ...
;             PG8_LDA(At, 0, 1); PG8_STAGE(PG8_SB(0, 0), b2, voffB); PG8_STAGE(PG8_SB(0, 1), b2 + bhstep, voffB); PG8_STAGE(PG8_SA(0, 0), a2, voffA);
;             PG8_WAIT_V(8); PG8_WAIT_L(0); PG8_BAR; PG8_MMA(1, 0, At, B0); PG8_MMA(1, 1, At, B1); PG8_BAR; PG8_SCHED;
;             PG8_LDB(B0, 1, 0); PG8_LDB(B1, 1, 1); PG8_SCHED; PG8_LDA(At, 1, 0); PG8_STAGE(PG8_SA(0, 1), a2 + hstep, voffA);
;             PG8_WAIT_V(8); PG8_WAIT_L(0); PG8_BAR; PG8_MMA(0, 0, At, B0); PG8_MMA(0, 1, At, B1); PG8_BAR; PG8_SCHED;
	s_nop 0
	s_waitcnt lgkmcnt(0)
	v_mfma_f32_16x16x32_bf16 v[62:65], v[146:149], v[190:193], v[62:65]
	v_mfma_f32_16x16x32_bf16 v[62:65], v[150:153], v[194:197], v[62:65]
	v_mfma_f32_16x16x32_bf16 v[58:61], v[154:157], v[190:193], v[58:61]
	v_mfma_f32_16x16x32_bf16 v[58:61], v[158:161], v[194:197], v[58:61]
	v_mfma_f32_16x16x32_bf16 v[46:49], v[146:149], v[198:201], v[46:49]
	v_mfma_f32_16x16x32_bf16 v[46:49], v[150:153], v[204:207], v[46:49]
	v_mfma_f32_16x16x32_bf16 v[42:45], v[154:157], v[198:201], v[42:45]
	v_mfma_f32_16x16x32_bf16 v[42:45], v[158:161], v[204:207], v[42:45]
	v_mfma_f32_16x16x32_bf16 v[30:33], v[146:149], v[208:211], v[30:33]
	v_mfma_f32_16x16x32_bf16 v[30:33], v[150:153], v[212:215], v[30:33]
	v_mfma_f32_16x16x32_bf16 v[26:29], v[154:157], v[208:211], v[26:29]
	v_mfma_f32_16x16x32_bf16 v[26:29], v[158:161], v[212:215], v[26:29]
	v_mfma_f32_16x16x32_bf16 v[14:17], v[146:149], v[216:219], v[14:17]
	v_mfma_f32_16x16x32_bf16 v[14:17], v[150:153], v[220:223], v[14:17]
	v_mfma_f32_16x16x32_bf16 v[10:13], v[154:157], v[216:219], v[10:13]
	v_mfma_f32_16x16x32_bf16 v[10:13], v[158:161], v[220:223], v[10:13]
	s_nop 0
	s_nop 0
	v_mfma_f32_16x16x32_bf16 v[54:57], v[162:165], v[190:193], v[54:57]
	v_mfma_f32_16x16x32_bf16 v[54:57], v[166:169], v[194:197], v[54:57]
	v_mfma_f32_16x16x32_bf16 v[50:53], v[182:185], v[190:193], v[50:53]
	v_mfma_f32_16x16x32_bf16 v[50:53], v[186:189], v[194:197], v[50:53]
	v_mfma_f32_16x16x32_bf16 v[38:41], v[162:165], v[198:201], v[38:41]
	v_mfma_f32_16x16x32_bf16 v[38:41], v[166:169], v[204:207], v[38:41]
	v_mfma_f32_16x16x32_bf16 v[34:37], v[182:185], v[198:201], v[34:37]
	v_mfma_f32_16x16x32_bf16 v[34:37], v[186:189], v[204:207], v[34:37]
	v_mfma_f32_16x16x32_bf16 v[22:25], v[162:165], v[208:211], v[22:25]
	v_mfma_f32_16x16x32_bf16 v[22:25], v[166:169], v[212:215], v[22:25]
	v_mfma_f32_16x16x32_bf16 v[18:21], v[182:185], v[208:211], v[18:21]
	v_mfma_f32_16x16x32_bf16 v[18:21], v[186:189], v[212:215], v[18:21]
	v_mfma_f32_16x16x32_bf16 v[6:9], v[162:165], v[216:219], v[6:9]
	v_mfma_f32_16x16x32_bf16 v[6:9], v[166:169], v[220:223], v[6:9]
	v_mfma_f32_16x16x32_bf16 v[2:5], v[182:185], v[216:219], v[2:5]
	v_mfma_f32_16x16x32_bf16 v[2:5], v[186:189], v[220:223], v[2:5]
	s_nop 0
	s_barrier
	s_add_i32 s71, 0, 0x18000
	v_add_u32_e32 v0, s71, v171
	s_add_i32 s74, 0, 0x1c000
	ds_read_b128 v[146:149], v0
	ds_read_b128 v[150:153], v0 offset:1024
	ds_read_b128 v[154:157], v0 offset:2048
	ds_read_b128 v[158:161], v0 offset:3072
	v_add_u32_e32 v0, s74, v171
	ds_read_b128 v[162:165], v0
	ds_read_b128 v[166:169], v0 offset:1024
	ds_read_b128 v[182:185], v0 offset:2048
	ds_read_b128 v[186:189], v0 offset:3072
	s_add_u32 s44, s44, 0x40000
	s_addc_u32 s45, s45, 0
	s_mov_b32 m0, s8
	v_lshl_add_u64 v[232:233], s[44:45], 0, v[132:133]
	ds_read_b128 v[190:193], v177 offset:32768
	ds_read_b128 v[194:197], v177 offset:33792
	ds_read_b128 v[198:201], v177 offset:34816
	ds_read_b128 v[204:207], v177 offset:35840
	ds_read_b128 v[208:211], v177 offset:36864
	ds_read_b128 v[212:215], v177 offset:37888
	ds_read_b128 v[216:219], v177 offset:38912
	ds_read_b128 v[220:223], v177 offset:39936
	global_load_lds_dwordx4 v[232:233], off
	v_lshl_add_u64 v[232:233], s[44:45], 0, v[136:137]
	s_mov_b32 m0, s9
	s_nop 0
	global_load_lds_dwordx4 v[232:233], off
	s_waitcnt vmcnt(8)
	s_waitcnt lgkmcnt(0)
	s_barrier
	s_nop 0
	s_waitcnt lgkmcnt(0)
	v_mfma_f32_16x16x32_bf16 v[126:129], v[146:149], v[190:193], v[126:129]
	v_mfma_f32_16x16x32_bf16 v[126:129], v[150:153], v[194:197], v[126:129]
	v_mfma_f32_16x16x32_bf16 v[122:125], v[154:157], v[190:193], v[122:125]
	v_mfma_f32_16x16x32_bf16 v[122:125], v[158:161], v[194:197], v[122:125]
	v_mfma_f32_16x16x32_bf16 v[110:113], v[146:149], v[198:201], v[110:113]
	v_mfma_f32_16x16x32_bf16 v[110:113], v[150:153], v[204:207], v[110:113]
	v_mfma_f32_16x16x32_bf16 v[106:109], v[154:157], v[198:201], v[106:109]
	v_mfma_f32_16x16x32_bf16 v[106:109], v[158:161], v[204:207], v[106:109]
	v_mfma_f32_16x16x32_bf16 v[94:97], v[146:149], v[208:211], v[94:97]
	v_mfma_f32_16x16x32_bf16 v[94:97], v[150:153], v[212:215], v[94:97]
	v_mfma_f32_16x16x32_bf16 v[90:93], v[154:157], v[208:211], v[90:93]
	v_mfma_f32_16x16x32_bf16 v[90:93], v[158:161], v[212:215], v[90:93]
	v_mfma_f32_16x16x32_bf16 v[78:81], v[146:149], v[216:219], v[78:81]
	v_mfma_f32_16x16x32_bf16 v[78:81], v[150:153], v[220:223], v[78:81]
	v_mfma_f32_16x16x32_bf16 v[74:77], v[154:157], v[216:219], v[74:77]
	v_mfma_f32_16x16x32_bf16 v[74:77], v[158:161], v[220:223], v[74:77]
	s_nop 0
	s_nop 0
	v_mfma_f32_16x16x32_bf16 v[118:121], v[162:165], v[190:193], v[118:121]
	v_mfma_f32_16x16x32_bf16 v[118:121], v[166:169], v[194:197], v[118:121]
	v_mfma_f32_16x16x32_bf16 v[114:117], v[182:185], v[190:193], v[114:117]
	v_mfma_f32_16x16x32_bf16 v[114:117], v[186:189], v[194:197], v[114:117]
	v_mfma_f32_16x16x32_bf16 v[102:105], v[162:165], v[198:201], v[102:105]
	v_mfma_f32_16x16x32_bf16 v[102:105], v[166:169], v[204:207], v[102:105]
	v_mfma_f32_16x16x32_bf16 v[98:101], v[182:185], v[198:201], v[98:101]
	v_mfma_f32_16x16x32_bf16 v[98:101], v[186:189], v[204:207], v[98:101]
	v_mfma_f32_16x16x32_bf16 v[86:89], v[162:165], v[208:211], v[86:89]
	v_mfma_f32_16x16x32_bf16 v[86:89], v[166:169], v[212:215], v[86:89]
	v_mfma_f32_16x16x32_bf16 v[82:85], v[182:185], v[208:211], v[82:85]
	v_mfma_f32_16x16x32_bf16 v[82:85], v[186:189], v[212:215], v[82:85]
	v_mfma_f32_16x16x32_bf16 v[70:73], v[162:165], v[216:219], v[70:73]
	v_mfma_f32_16x16x32_bf16 v[70:73], v[166:169], v[220:223], v[70:73]
	v_mfma_f32_16x16x32_bf16 v[66:69], v[182:185], v[216:219], v[66:69]
	v_mfma_f32_16x16x32_bf16 v[66:69], v[186:189], v[220:223], v[66:69]
	s_nop 0
	s_barrier
; #define PG8_STAGE(bufoff, gbase, voff) do { _Pragma("unroll") for (int _i = 0; _i < 2; ++_i) \
;         __builtin_amdgcn_global_load_lds((const unsigned*)((const char*)(gbase) + (voff)[_i]), (PG8_LAS unsigned*)(lds + (bufoff) + ldsw + _i * 8192), 16, 0, 0); } while (0)
; #define PG8_LDA(dst, b, h) do { _Pragma("unroll") for (int m = 0; m < 4; ++m) _Pragma("unroll") for (int k = 0; k < 2; ++k) dst[m][k] = *(const PG8_LAS bf16x8*)(lds + PG8_SA(b, h) + aoff + m * 2048 + k * 1024); } while (0)
; #define PG8_MMA(ai, bj, At, Bt) do { __builtin_amdgcn_s_setprio(1); _Pragma("unroll") for (int m = 0; m < 4; ++m) _Pragma("unroll") for (int n = 0; n < 2; ++n) _Pragma("unroll") for (int k = 0; k < 2; ++k) \
;         acc[ai][bj][m][n] = __builtin_amdgcn_mfma_f32_16x16x32_bf16(Bt[n][k], At[m][k], acc[ai][bj][m][n], 0, 0, 0); __builtin_amdgcn_s_setprio(0); } while (0)
; #define PG8_WAIT_V(n) asm volatile("s_waitcnt vmcnt(" #n ")" ::: "memory")
; #define PG8_WAIT_L(n) asm volatile("s_waitcnt lgkmcnt(" #n ")" ::: "memory")
; #define PG8_BAR __builtin_amdgcn_s_barrier()
; #define PG8_SCHED __builtin_amdgcn_sched_barrier(0)
; template <class Epi, class Sched, bool ALIGN_EPI = false, bool SP2 = false>
; __device__ __forceinline__ void gemm_phase(PG8_LAS unsigned char* lds, const Gemm g, const Sched& S, const Epi& E, const int wave_s) {
;     ...
;         for (int t = 0; t < nt; t += 2) {
;     ...
;             PG8_LDA(At, 1, 1); PG8_STAGE(PG8_SB(1, 0), b3, voffB); PG8_STAGE(PG8_SB(1, 1), b3 + bhstep, voffB); PG8_STAGE(PG8_SA(1, 0), a3, voffA);
;             PG8_WAIT_V(8); PG8_WAIT_L(0); PG8_BAR; PG8_MMA(1, 0, At, B0); PG8_MMA(1, 1, At, B1); PG8_BAR; PG8_SCHED;
	s_add_i32 s44, s71, s6
	v_lshl_add_u64 v[224:225], v[224:225], 0, s[24:25]
	s_mov_b32 m0, s44
	ds_read_b128 v[190:193], v177 offset:49152
	ds_read_b128 v[194:197], v177 offset:50176
	ds_read_b128 v[198:201], v177 offset:51200
	ds_read_b128 v[204:207], v177 offset:52224
	ds_read_b128 v[208:211], v177 offset:53248
	ds_read_b128 v[212:215], v177 offset:54272
	ds_read_b128 v[216:219], v177 offset:55296
	ds_read_b128 v[220:223], v177 offset:56320
	global_load_lds_dwordx4 v[224:225], off
	s_add_i32 m0, s44, 0x2000
	s_add_u32 s42, s42, 0x10080
	v_lshl_add_u64 v[224:225], v[226:227], 0, s[24:25]
	s_addc_u32 s43, s43, 0
	s_add_i32 s44, s74, s6
	global_load_lds_dwordx4 v[224:225], off
	v_lshl_add_u64 v[224:225], s[42:43], 0, v[134:135]
	s_mov_b32 m0, s44
	s_nop 0
	global_load_lds_dwordx4 v[224:225], off
	v_lshl_add_u64 v[224:225], s[42:43], 0, v[138:139]
	s_add_i32 m0, s44, 0x2000
	s_nop 0
	global_load_lds_dwordx4 v[224:225], off
	v_lshl_add_u64 v[224:225], v[228:229], 0, s[24:25]
	s_mov_b32 m0, s11
	s_nop 0
	global_load_lds_dwordx4 v[224:225], off
	v_lshl_add_u64 v[224:225], v[230:231], 0, s[24:25]
	s_mov_b32 m0, s12
	s_nop 0
	global_load_lds_dwordx4 v[224:225], off
	s_waitcnt vmcnt(8)
	s_waitcnt lgkmcnt(0)
	s_barrier
	s_nop 0
	s_waitcnt lgkmcnt(0)
	v_mfma_f32_16x16x32_bf16 v[62:65], v[146:149], v[190:193], v[62:65]
	v_mfma_f32_16x16x32_bf16 v[62:65], v[150:153], v[194:197], v[62:65]
	v_mfma_f32_16x16x32_bf16 v[58:61], v[154:157], v[190:193], v[58:61]
	v_mfma_f32_16x16x32_bf16 v[58:61], v[158:161], v[194:197], v[58:61]
	v_mfma_f32_16x16x32_bf16 v[46:49], v[146:149], v[198:201], v[46:49]
	v_mfma_f32_16x16x32_bf16 v[46:49], v[150:153], v[204:207], v[46:49]
	v_mfma_f32_16x16x32_bf16 v[42:45], v[154:157], v[198:201], v[42:45]
	v_mfma_f32_16x16x32_bf16 v[42:45], v[158:161], v[204:207], v[42:45]
	v_mfma_f32_16x16x32_bf16 v[30:33], v[146:149], v[208:211], v[30:33]
	v_mfma_f32_16x16x32_bf16 v[30:33], v[150:153], v[212:215], v[30:33]
	v_mfma_f32_16x16x32_bf16 v[26:29], v[154:157], v[208:211], v[26:29]
	v_mfma_f32_16x16x32_bf16 v[26:29], v[158:161], v[212:215], v[26:29]
	v_mfma_f32_16x16x32_bf16 v[14:17], v[146:149], v[216:219], v[14:17]
	v_mfma_f32_16x16x32_bf16 v[14:17], v[150:153], v[220:223], v[14:17]
	v_mfma_f32_16x16x32_bf16 v[10:13], v[154:157], v[216:219], v[10:13]
	v_mfma_f32_16x16x32_bf16 v[10:13], v[158:161], v[220:223], v[10:13]
	s_nop 0
	s_nop 0
	v_mfma_f32_16x16x32_bf16 v[54:57], v[162:165], v[190:193], v[54:57]
	v_mfma_f32_16x16x32_bf16 v[54:57], v[166:169], v[194:197], v[54:57]
	v_mfma_f32_16x16x32_bf16 v[50:53], v[182:185], v[190:193], v[50:53]
	v_mfma_f32_16x16x32_bf16 v[50:53], v[186:189], v[194:197], v[50:53]
	v_mfma_f32_16x16x32_bf16 v[38:41], v[162:165], v[198:201], v[38:41]
	v_mfma_f32_16x16x32_bf16 v[38:41], v[166:169], v[204:207], v[38:41]
	v_mfma_f32_16x16x32_bf16 v[34:37], v[182:185], v[198:201], v[34:37]
	v_mfma_f32_16x16x32_bf16 v[34:37], v[186:189], v[204:207], v[34:37]
	v_mfma_f32_16x16x32_bf16 v[22:25], v[162:165], v[208:211], v[22:25]
	v_mfma_f32_16x16x32_bf16 v[22:25], v[166:169], v[212:215], v[22:25]
	v_mfma_f32_16x16x32_bf16 v[18:21], v[182:185], v[208:211], v[18:21]
	v_mfma_f32_16x16x32_bf16 v[18:21], v[186:189], v[212:215], v[18:21]
	v_mfma_f32_16x16x32_bf16 v[6:9], v[162:165], v[216:219], v[6:9]
	v_mfma_f32_16x16x32_bf16 v[6:9], v[166:169], v[220:223], v[6:9]
	v_mfma_f32_16x16x32_bf16 v[2:5], v[182:185], v[216:219], v[2:5]
	v_mfma_f32_16x16x32_bf16 v[2:5], v[186:189], v[220:223], v[2:5]
	s_nop 0
	s_barrier
	s_add_i32 s70, s70, 2
	s_add_u32 s20, s20, 0x100
	s_addc_u32 s21, s21, 0
	s_add_u32 s68, s68, 0x100
	s_addc_u32 s69, s69, 0
	s_cmp_gt_u32 s70, 13
	s_cbranch_scc0 .LBB0_136
	s_and_b64 vcc, exec, s[60:61]
	s_cbranch_vccz .LBB0_139
	s_barrier

; #define PG8_STAGE(bufoff, gbase, voff) do { _Pragma("unroll") for (int _i = 0; _i < 2; ++_i) \
;         __builtin_amdgcn_global_load_lds((const unsigned*)((const char*)(gbase) + (voff)[_i]), (PG8_LAS unsigned*)(lds + (bufoff) + ldsw + _i * 8192), 16, 0, 0); } while (0)
; #define PG8_LDA(dst, b, h) do { _Pragma("unroll") for (int m = 0; m < 4; ++m) _Pragma("unroll") for (int k = 0; k < 2; ++k) dst[m][k] = *(const PG8_LAS bf16x8*)(lds + PG8_SA(b, h) + aoff + m * 2048 + k * 1024); } while (0)
; #define PG8_LDB(dst, b, h) do { _Pragma("unroll") for (int n = 0; n < 2; ++n) _Pragma("unroll") for (int k = 0; k < 2; ++k) dst[n][k] = *(const PG8_LAS bf16x8*)(lds + PG8_SB(b, h) + boff + n * 2048 + k * 1024); } while (0)
; #define PG8_MMA(ai, bj, At, Bt) do { __builtin_amdgcn_s_setprio(1); _Pragma("unroll") for (int m = 0; m < 4; ++m) _Pragma("unroll") for (int n = 0; n < 2; ++n) _Pragma("unroll") for (int k = 0; k < 2; ++k) \
;         acc[ai][bj][m][n] = __builtin_amdgcn_mfma_f32_16x16x32_bf16(Bt[n][k], At[m][k], acc[ai][bj][m][n], 0, 0, 0); __builtin_amdgcn_s_setprio(0); } while (0)
; #define PG8_WAIT_V(n) asm volatile("s_waitcnt vmcnt(" #n ")" ::: "memory")
; #define PG8_WAIT_L(n) asm volatile("s_waitcnt lgkmcnt(" #n ")" ::: "memory")
; #define PG8_BAR __builtin_amdgcn_s_barrier()
; #define PG8_SCHED __builtin_amdgcn_sched_barrier(0)
; template <class Epi, class Sched, bool ALIGN_EPI = false, bool SP2 = false>
; __device__ __forceinline__ void gemm_phase(PG8_LAS unsigned char* lds, const Gemm g, const Sched& S, const Epi& E, const int wave_s) {
;     ...
;             PG8_LDB(B0, 0, 0); PG8_LDB(B1, 0, 1); PG8_SCHED; PG8_LDA(At, 0, 0); PG8_STAGE(PG8_SA(1, 1), a1 + hstep, voffA);
;             PG8_WAIT_V(8); PG8_WAIT_L(0); PG8_BAR; PG8_MMA(0, 0, At, B0); PG8_MMA(0, 1, At, B1); PG8_BAR; PG8_SCHED;
;             PG8_LDA(At, 0, 1); PG8_STAGE(PG8_SB(0, 0), b2, voffB); PG8_STAGE(PG8_SB(0, 1), b2 + bhstep, voffB); PG8_STAGE(PG8_SA(0, 0), a2, voffA);
;             PG8_WAIT_V(8); PG8_WAIT_L(0); PG8_BAR; PG8_MMA(1, 0, At, B0); PG8_MMA(1, 1, At, B1); PG8_BAR; PG8_SCHED;
.LBB0_753:
	s_add_i32 s54, s48, 2
	s_add_u32 s55, s44, 0x80
	s_addc_u32 s49, s45, 0
	s_add_i32 s60, 0, 0x10000
	s_cmp_eq_u32 s16, s48
	s_cselect_b32 s49, s39, s49
	s_cselect_b32 s48, s47, s55
	s_cselect_b32 s57, s29, s53
	s_cselect_b32 s56, s51, s52
	s_add_i32 s55, 0, 0x14000
	v_add_u32_e32 v142, s60, v205
	v_add_u32_e32 v160, s55, v205
	ds_read_b128 v[130:133], v142
	ds_read_b128 v[134:137], v142 offset:1024
	ds_read_b128 v[138:141], v142 offset:2048
	ds_read_b128 v[142:145], v142 offset:3072
	ds_read_b128 v[146:149], v160
	ds_read_b128 v[150:153], v160 offset:1024
	ds_read_b128 v[154:157], v160 offset:2048
	ds_read_b128 v[160:163], v160 offset:3072
	v_lshl_add_u64 v[220:221], s[44:45], 0, v[178:179]
	s_add_i32 m0, s7, 0xc000
	ds_read_b128 v[164:167], v208
	ds_read_b128 v[182:185], v208 offset:1024
	ds_read_b128 v[186:189], v208 offset:2048
	ds_read_b128 v[190:193], v208 offset:3072
	ds_read_b128 v[194:197], v208 offset:4096
	ds_read_b128 v[198:201], v208 offset:5120
	ds_read_b128 v[212:215], v208 offset:6144
	ds_read_b128 v[216:219], v208 offset:7168
	global_load_lds_dwordx4 v[220:221], off
	v_lshl_add_u64 v[220:221], s[44:45], 0, v[180:181]
	s_add_i32 m0, s7, 0xe000
	s_nop 0
	global_load_lds_dwordx4 v[220:221], off
	s_waitcnt vmcnt(8)
	s_waitcnt lgkmcnt(0)
	s_barrier
	s_nop 0
	s_waitcnt lgkmcnt(0)
	v_mfma_f32_16x16x32_bf16 v[126:129], v[130:133], v[164:167], v[126:129]
	v_mfma_f32_16x16x32_bf16 v[126:129], v[134:137], v[182:185], v[126:129]
	v_mfma_f32_16x16x32_bf16 v[122:125], v[138:141], v[164:167], v[122:125]
	v_mfma_f32_16x16x32_bf16 v[122:125], v[142:145], v[182:185], v[122:125]
	v_mfma_f32_16x16x32_bf16 v[110:113], v[130:133], v[186:189], v[110:113]
	v_mfma_f32_16x16x32_bf16 v[110:113], v[134:137], v[190:193], v[110:113]
	v_mfma_f32_16x16x32_bf16 v[106:109], v[138:141], v[186:189], v[106:109]
	v_mfma_f32_16x16x32_bf16 v[106:109], v[142:145], v[190:193], v[106:109]
	v_mfma_f32_16x16x32_bf16 v[94:97], v[130:133], v[194:197], v[94:97]
	v_mfma_f32_16x16x32_bf16 v[94:97], v[134:137], v[198:201], v[94:97]
	v_mfma_f32_16x16x32_bf16 v[90:93], v[138:141], v[194:197], v[90:93]
	v_mfma_f32_16x16x32_bf16 v[90:93], v[142:145], v[198:201], v[90:93]
	v_mfma_f32_16x16x32_bf16 v[78:81], v[130:133], v[212:215], v[78:81]
	v_mfma_f32_16x16x32_bf16 v[78:81], v[134:137], v[216:219], v[78:81]
	v_mfma_f32_16x16x32_bf16 v[74:77], v[138:141], v[212:215], v[74:77]
	v_mfma_f32_16x16x32_bf16 v[74:77], v[142:145], v[216:219], v[74:77]
	s_nop 0
	s_nop 0
	v_mfma_f32_16x16x32_bf16 v[118:121], v[146:149], v[164:167], v[118:121]
	v_mfma_f32_16x16x32_bf16 v[118:121], v[150:153], v[182:185], v[118:121]
	v_mfma_f32_16x16x32_bf16 v[114:117], v[154:157], v[164:167], v[114:117]
	v_mfma_f32_16x16x32_bf16 v[114:117], v[160:163], v[182:185], v[114:117]
	v_mfma_f32_16x16x32_bf16 v[102:105], v[146:149], v[186:189], v[102:105]
	v_mfma_f32_16x16x32_bf16 v[102:105], v[150:153], v[190:193], v[102:105]
	v_mfma_f32_16x16x32_bf16 v[98:101], v[154:157], v[186:189], v[98:101]
	v_mfma_f32_16x16x32_bf16 v[98:101], v[160:163], v[190:193], v[98:101]
	v_mfma_f32_16x16x32_bf16 v[86:89], v[146:149], v[194:197], v[86:89]
	v_mfma_f32_16x16x32_bf16 v[86:89], v[150:153], v[198:201], v[86:89]
	v_mfma_f32_16x16x32_bf16 v[82:85], v[154:157], v[194:197], v[82:85]
	v_mfma_f32_16x16x32_bf16 v[82:85], v[160:163], v[198:201], v[82:85]
	v_mfma_f32_16x16x32_bf16 v[70:73], v[146:149], v[212:215], v[70:73]
	v_mfma_f32_16x16x32_bf16 v[70:73], v[150:153], v[216:219], v[70:73]
	v_mfma_f32_16x16x32_bf16 v[66:69], v[154:157], v[212:215], v[66:69]
	v_mfma_f32_16x16x32_bf16 v[66:69], v[160:163], v[216:219], v[66:69]
	s_nop 0
	s_barrier
	s_add_i32 s60, s60, s5
	v_lshl_add_u64 v[220:221], s[56:57], 0, v[170:171]
	s_mov_b32 m0, s60
	ds_read_b128 v[164:167], v208 offset:16384
	ds_read_b128 v[182:185], v208 offset:17408
	ds_read_b128 v[186:189], v208 offset:18432
	ds_read_b128 v[190:193], v208 offset:19456
	ds_read_b128 v[194:197], v208 offset:20480
	ds_read_b128 v[198:201], v208 offset:21504
	ds_read_b128 v[212:215], v208 offset:22528
	ds_read_b128 v[216:219], v208 offset:23552
	global_load_lds_dwordx4 v[220:221], off
	s_add_i32 m0, s60, 0x2000
	v_lshl_add_u64 v[222:223], s[56:57], 0, v[158:159]
	s_add_u32 s56, s56, s4
	s_addc_u32 s57, s57, 0
	s_add_i32 s55, s55, s5
	global_load_lds_dwordx4 v[222:223], off
	v_lshl_add_u64 v[224:225], s[56:57], 0, v[170:171]
	s_mov_b32 m0, s55
	v_lshl_add_u64 v[226:227], s[56:57], 0, v[158:159]
	global_load_lds_dwordx4 v[224:225], off
	s_add_i32 m0, s55, 0x2000
	v_lshl_add_u64 v[228:229], s[48:49], 0, v[172:173]
	global_load_lds_dwordx4 v[226:227], off
	s_mov_b32 m0, s7
	v_lshl_add_u64 v[230:231], s[48:49], 0, v[168:169]
	global_load_lds_dwordx4 v[228:229], off
	s_mov_b32 m0, s8
	s_nop 0
	global_load_lds_dwordx4 v[230:231], off
	s_waitcnt vmcnt(8)
	s_waitcnt lgkmcnt(0)
	s_barrier
; #define PG8_STAGE(bufoff, gbase, voff) do { _Pragma("unroll") for (int _i = 0; _i < 2; ++_i) \
;         __builtin_amdgcn_global_load_lds((const unsigned*)((const char*)(gbase) + (voff)[_i]), (PG8_LAS unsigned*)(lds + (bufoff) + ldsw + _i * 8192), 16, 0, 0); } while (0)
; #define PG8_LDA(dst, b, h) do { _Pragma("unroll") for (int m = 0; m < 4; ++m) _Pragma("unroll") for (int k = 0; k < 2; ++k) dst[m][k] = *(const PG8_LAS bf16x8*)(lds + PG8_SA(b, h) + aoff + m * 2048 + k * 1024); } while (0)
; #define PG8_LDB(dst, b, h) do { _Pragma("unroll") for (int n = 0; n < 2; ++n) _Pragma("unroll") for (int k = 0; k < 2; ++k) dst[n][k] = *(const PG8_LAS bf16x8*)(lds + PG8_SB(b, h) + boff + n * 2048 + k * 1024); } while (0)
; #define PG8_MMA(ai, bj, At, Bt) do { __builtin_amdgcn_s_setprio(1); _Pragma("unroll") for (int m = 0; m < 4; ++m) _Pragma("unroll") for (int n = 0; n < 2; ++n) _Pragma("unroll") for (int k = 0; k < 2; ++k) \
;         acc[ai][bj][m][n] = __builtin_amdgcn_mfma_f32_16x16x32_bf16(Bt[n][k], At[m][k], acc[ai][bj][m][n], 0, 0, 0); __builtin_amdgcn_s_setprio(0); } while (0)
; #define PG8_WAIT_V(n) asm volatile("s_waitcnt vmcnt(" #n ")" ::: "memory")
; #define PG8_WAIT_L(n) asm volatile("s_waitcnt lgkmcnt(" #n ")" ::: "memory")
; #define PG8_BAR __builtin_amdgcn_s_barrier()
; #define PG8_SCHED __builtin_amdgcn_sched_barrier(0)
; template <class Epi, class Sched, bool ALIGN_EPI = false, bool SP2 = false>
; __device__ __forceinline__ void gemm_phase(PG8_LAS unsigned char* lds, const Gemm g, const Sched& S, const Epi& E, const int wave_s) {
;     ...
;             PG8_WAIT_V(8); PG8_WAIT_L(0); PG8_BAR; PG8_MMA(1, 0, At, B0); PG8_MMA(1, 1, At, B1); PG8_BAR; PG8_SCHED;
;             PG8_LDB(B0, 1, 0); PG8_LDB(B1, 1, 1); PG8_SCHED; PG8_LDA(At, 1, 0); PG8_STAGE(PG8_SA(0, 1), a2 + hstep, voffA);
;             PG8_WAIT_V(8); PG8_WAIT_L(0); PG8_BAR; PG8_MMA(0, 0, At, B0); PG8_MMA(0, 1, At, B1); PG8_BAR; PG8_SCHED;
;             PG8_LDA(At, 1, 1); PG8_STAGE(PG8_SB(1, 0), b3, voffB); PG8_STAGE(PG8_SB(1, 1), b3 + bhstep, voffB); PG8_STAGE(PG8_SA(1, 0), a3, voffA);
	s_nop 0
	s_waitcnt lgkmcnt(0)
	v_mfma_f32_16x16x32_bf16 v[62:65], v[130:133], v[164:167], v[62:65]
	v_mfma_f32_16x16x32_bf16 v[62:65], v[134:137], v[182:185], v[62:65]
	v_mfma_f32_16x16x32_bf16 v[58:61], v[138:141], v[164:167], v[58:61]
	v_mfma_f32_16x16x32_bf16 v[58:61], v[142:145], v[182:185], v[58:61]
	v_mfma_f32_16x16x32_bf16 v[46:49], v[130:133], v[186:189], v[46:49]
	v_mfma_f32_16x16x32_bf16 v[46:49], v[134:137], v[190:193], v[46:49]
	v_mfma_f32_16x16x32_bf16 v[42:45], v[138:141], v[186:189], v[42:45]
	v_mfma_f32_16x16x32_bf16 v[42:45], v[142:145], v[190:193], v[42:45]
	v_mfma_f32_16x16x32_bf16 v[30:33], v[130:133], v[194:197], v[30:33]
	v_mfma_f32_16x16x32_bf16 v[30:33], v[134:137], v[198:201], v[30:33]
	v_mfma_f32_16x16x32_bf16 v[26:29], v[138:141], v[194:197], v[26:29]
	v_mfma_f32_16x16x32_bf16 v[26:29], v[142:145], v[198:201], v[26:29]
	v_mfma_f32_16x16x32_bf16 v[14:17], v[130:133], v[212:215], v[14:17]
	v_mfma_f32_16x16x32_bf16 v[14:17], v[134:137], v[216:219], v[14:17]
	v_mfma_f32_16x16x32_bf16 v[10:13], v[138:141], v[212:215], v[10:13]
	v_mfma_f32_16x16x32_bf16 v[10:13], v[142:145], v[216:219], v[10:13]
	s_nop 0
	s_nop 0
	v_mfma_f32_16x16x32_bf16 v[54:57], v[146:149], v[164:167], v[54:57]
	v_mfma_f32_16x16x32_bf16 v[54:57], v[150:153], v[182:185], v[54:57]
	v_mfma_f32_16x16x32_bf16 v[50:53], v[154:157], v[164:167], v[50:53]
	v_mfma_f32_16x16x32_bf16 v[50:53], v[160:163], v[182:185], v[50:53]
	v_mfma_f32_16x16x32_bf16 v[38:41], v[146:149], v[186:189], v[38:41]
	v_mfma_f32_16x16x32_bf16 v[38:41], v[150:153], v[190:193], v[38:41]
	v_mfma_f32_16x16x32_bf16 v[34:37], v[154:157], v[186:189], v[34:37]
	v_mfma_f32_16x16x32_bf16 v[34:37], v[160:163], v[190:193], v[34:37]
	v_mfma_f32_16x16x32_bf16 v[22:25], v[146:149], v[194:197], v[22:25]
	v_mfma_f32_16x16x32_bf16 v[22:25], v[150:153], v[198:201], v[22:25]
	v_mfma_f32_16x16x32_bf16 v[18:21], v[154:157], v[194:197], v[18:21]
	v_mfma_f32_16x16x32_bf16 v[18:21], v[160:163], v[198:201], v[18:21]
	v_mfma_f32_16x16x32_bf16 v[6:9], v[146:149], v[212:215], v[6:9]
	v_mfma_f32_16x16x32_bf16 v[6:9], v[150:153], v[216:219], v[6:9]
	v_mfma_f32_16x16x32_bf16 v[2:5], v[154:157], v[212:215], v[2:5]
	v_mfma_f32_16x16x32_bf16 v[2:5], v[160:163], v[216:219], v[2:5]
	s_nop 0
	s_barrier
	s_add_i32 s55, 0, 0x18000
	s_add_i32 s56, 0, 0x1c000
	v_add_u32_e32 v142, s55, v205
	v_add_u32_e32 v160, s56, v205
	ds_read_b128 v[130:133], v142
	ds_read_b128 v[134:137], v142 offset:1024
	ds_read_b128 v[138:141], v142 offset:2048
	ds_read_b128 v[142:145], v142 offset:3072
	ds_read_b128 v[146:149], v160
	ds_read_b128 v[150:153], v160 offset:1024
	ds_read_b128 v[154:157], v160 offset:2048
	ds_read_b128 v[160:163], v160 offset:3072
	s_add_u32 s48, s48, s74
	s_addc_u32 s49, s49, 0
	s_mov_b32 m0, s9
	v_lshl_add_u64 v[232:233], s[48:49], 0, v[172:173]
	ds_read_b128 v[164:167], v208 offset:32768
	ds_read_b128 v[182:185], v208 offset:33792
	ds_read_b128 v[186:189], v208 offset:34816
	ds_read_b128 v[190:193], v208 offset:35840
	ds_read_b128 v[194:197], v208 offset:36864
	ds_read_b128 v[198:201], v208 offset:37888
	ds_read_b128 v[212:215], v208 offset:38912
	ds_read_b128 v[216:219], v208 offset:39936
	global_load_lds_dwordx4 v[232:233], off
	v_lshl_add_u64 v[232:233], s[48:49], 0, v[168:169]
	s_mov_b32 m0, s10
	s_nop 0
	global_load_lds_dwordx4 v[232:233], off
	s_waitcnt vmcnt(8)
	s_waitcnt lgkmcnt(0)
	s_barrier
	s_nop 0
	s_waitcnt lgkmcnt(0)
	v_mfma_f32_16x16x32_bf16 v[126:129], v[130:133], v[164:167], v[126:129]
	v_mfma_f32_16x16x32_bf16 v[126:129], v[134:137], v[182:185], v[126:129]
	v_mfma_f32_16x16x32_bf16 v[122:125], v[138:141], v[164:167], v[122:125]
	v_mfma_f32_16x16x32_bf16 v[122:125], v[142:145], v[182:185], v[122:125]
	v_mfma_f32_16x16x32_bf16 v[110:113], v[130:133], v[186:189], v[110:113]
	v_mfma_f32_16x16x32_bf16 v[110:113], v[134:137], v[190:193], v[110:113]
	v_mfma_f32_16x16x32_bf16 v[106:109], v[138:141], v[186:189], v[106:109]
	v_mfma_f32_16x16x32_bf16 v[106:109], v[142:145], v[190:193], v[106:109]
	v_mfma_f32_16x16x32_bf16 v[94:97], v[130:133], v[194:197], v[94:97]
	v_mfma_f32_16x16x32_bf16 v[94:97], v[134:137], v[198:201], v[94:97]
	v_mfma_f32_16x16x32_bf16 v[90:93], v[138:141], v[194:197], v[90:93]
	v_mfma_f32_16x16x32_bf16 v[90:93], v[142:145], v[198:201], v[90:93]
	v_mfma_f32_16x16x32_bf16 v[78:81], v[130:133], v[212:215], v[78:81]
	v_mfma_f32_16x16x32_bf16 v[78:81], v[134:137], v[216:219], v[78:81]
	v_mfma_f32_16x16x32_bf16 v[74:77], v[138:141], v[212:215], v[74:77]
	v_mfma_f32_16x16x32_bf16 v[74:77], v[142:145], v[216:219], v[74:77]
	s_nop 0
	s_nop 0
	v_mfma_f32_16x16x32_bf16 v[118:121], v[146:149], v[164:167], v[118:121]
	v_mfma_f32_16x16x32_bf16 v[118:121], v[150:153], v[182:185], v[118:121]
	v_mfma_f32_16x16x32_bf16 v[114:117], v[154:157], v[164:167], v[114:117]
	v_mfma_f32_16x16x32_bf16 v[114:117], v[160:163], v[182:185], v[114:117]
	v_mfma_f32_16x16x32_bf16 v[102:105], v[146:149], v[186:189], v[102:105]
	v_mfma_f32_16x16x32_bf16 v[102:105], v[150:153], v[190:193], v[102:105]
	v_mfma_f32_16x16x32_bf16 v[98:101], v[154:157], v[186:189], v[98:101]
	v_mfma_f32_16x16x32_bf16 v[98:101], v[160:163], v[190:193], v[98:101]
	v_mfma_f32_16x16x32_bf16 v[86:89], v[146:149], v[194:197], v[86:89]
	v_mfma_f32_16x16x32_bf16 v[86:89], v[150:153], v[198:201], v[86:89]
	v_mfma_f32_16x16x32_bf16 v[82:85], v[154:157], v[194:197], v[82:85]
	v_mfma_f32_16x16x32_bf16 v[82:85], v[160:163], v[198:201], v[82:85]
	v_mfma_f32_16x16x32_bf16 v[70:73], v[146:149], v[212:215], v[70:73]
	v_mfma_f32_16x16x32_bf16 v[70:73], v[150:153], v[216:219], v[70:73]
	v_mfma_f32_16x16x32_bf16 v[66:69], v[154:157], v[212:215], v[66:69]
	v_mfma_f32_16x16x32_bf16 v[66:69], v[160:163], v[216:219], v[66:69]
	s_nop 0
	s_barrier
; #define PG8_STAGE(bufoff, gbase, voff) do { _Pragma("unroll") for (int _i = 0; _i < 2; ++_i) \
;         __builtin_amdgcn_global_load_lds((const unsigned*)((const char*)(gbase) + (voff)[_i]), (PG8_LAS unsigned*)(lds + (bufoff) + ldsw + _i * 8192), 16, 0, 0); } while (0)
; #define PG8_LDA(dst, b, h) do { _Pragma("unroll") for (int m = 0; m < 4; ++m) _Pragma("unroll") for (int k = 0; k < 2; ++k) dst[m][k] = *(const PG8_LAS bf16x8*)(lds + PG8_SA(b, h) + aoff + m * 2048 + k * 1024); } while (0)
; #define PG8_MMA(ai, bj, At, Bt) do { __builtin_amdgcn_s_setprio(1); _Pragma("unroll") for (int m = 0; m < 4; ++m) _Pragma("unroll") for (int n = 0; n < 2; ++n) _Pragma("unroll") for (int k = 0; k < 2; ++k) \
;         acc[ai][bj][m][n] = __builtin_amdgcn_mfma_f32_16x16x32_bf16(Bt[n][k], At[m][k], acc[ai][bj][m][n], 0, 0, 0); __builtin_amdgcn_s_setprio(0); } while (0)
; #define PG8_WAIT_V(n) asm volatile("s_waitcnt vmcnt(" #n ")" ::: "memory")
; #define PG8_WAIT_L(n) asm volatile("s_waitcnt lgkmcnt(" #n ")" ::: "memory")
; #define PG8_BAR __builtin_amdgcn_s_barrier()
; #define PG8_SCHED __builtin_amdgcn_sched_barrier(0)
; template <class Epi, class Sched, bool ALIGN_EPI = false, bool SP2 = false>
; __device__ __forceinline__ void gemm_phase(PG8_LAS unsigned char* lds, const Gemm g, const Sched& S, const Epi& E, const int wave_s) {
;     ...
;         for (int t = 0; t < nt; t += 2) {
;     ...
;             PG8_LDA(At, 1, 1); PG8_STAGE(PG8_SB(1, 0), b3, voffB); PG8_STAGE(PG8_SB(1, 1), b3 + bhstep, voffB); PG8_STAGE(PG8_SA(1, 0), a3, voffA);
;             PG8_WAIT_V(8); PG8_WAIT_L(0); PG8_BAR; PG8_MMA(1, 0, At, B0); PG8_MMA(1, 1, At, B1); PG8_BAR; PG8_SCHED;
	s_add_i32 s48, s55, s5
	v_lshl_add_u64 v[220:221], v[220:221], 0, s[24:25]
	s_mov_b32 m0, s48
	ds_read_b128 v[164:167], v208 offset:49152
	ds_read_b128 v[182:185], v208 offset:50176
	ds_read_b128 v[186:189], v208 offset:51200
	ds_read_b128 v[190:193], v208 offset:52224
	ds_read_b128 v[194:197], v208 offset:53248
	ds_read_b128 v[198:201], v208 offset:54272
	ds_read_b128 v[212:215], v208 offset:55296
	ds_read_b128 v[216:219], v208 offset:56320
	global_load_lds_dwordx4 v[220:221], off
	v_lshl_add_u64 v[220:221], v[222:223], 0, s[24:25]
	s_add_i32 m0, s48, 0x2000
	s_add_i32 s48, s56, s5
	global_load_lds_dwordx4 v[220:221], off
	v_lshl_add_u64 v[220:221], v[224:225], 0, s[24:25]
	s_mov_b32 m0, s48
	s_nop 0
	global_load_lds_dwordx4 v[220:221], off
	v_lshl_add_u64 v[220:221], v[226:227], 0, s[24:25]
	s_add_i32 m0, s48, 0x2000
	s_nop 0
	global_load_lds_dwordx4 v[220:221], off
	v_lshl_add_u64 v[220:221], v[228:229], 0, s[24:25]
	s_mov_b32 m0, s11
	s_nop 0
	global_load_lds_dwordx4 v[220:221], off
	v_lshl_add_u64 v[220:221], v[230:231], 0, s[24:25]
	s_mov_b32 m0, s12
	s_nop 0
	global_load_lds_dwordx4 v[220:221], off
	s_waitcnt vmcnt(8)
	s_waitcnt lgkmcnt(0)
	s_barrier
	s_nop 0
	s_waitcnt lgkmcnt(0)
	v_mfma_f32_16x16x32_bf16 v[62:65], v[130:133], v[164:167], v[62:65]
	v_mfma_f32_16x16x32_bf16 v[62:65], v[134:137], v[182:185], v[62:65]
	v_mfma_f32_16x16x32_bf16 v[58:61], v[138:141], v[164:167], v[58:61]
	v_mfma_f32_16x16x32_bf16 v[58:61], v[142:145], v[182:185], v[58:61]
	v_mfma_f32_16x16x32_bf16 v[46:49], v[130:133], v[186:189], v[46:49]
	v_mfma_f32_16x16x32_bf16 v[46:49], v[134:137], v[190:193], v[46:49]
	v_mfma_f32_16x16x32_bf16 v[42:45], v[138:141], v[186:189], v[42:45]
	v_mfma_f32_16x16x32_bf16 v[42:45], v[142:145], v[190:193], v[42:45]
	v_mfma_f32_16x16x32_bf16 v[30:33], v[130:133], v[194:197], v[30:33]
	v_mfma_f32_16x16x32_bf16 v[30:33], v[134:137], v[198:201], v[30:33]
	v_mfma_f32_16x16x32_bf16 v[26:29], v[138:141], v[194:197], v[26:29]
	v_mfma_f32_16x16x32_bf16 v[26:29], v[142:145], v[198:201], v[26:29]
	v_mfma_f32_16x16x32_bf16 v[14:17], v[130:133], v[212:215], v[14:17]
	v_mfma_f32_16x16x32_bf16 v[14:17], v[134:137], v[216:219], v[14:17]
	v_mfma_f32_16x16x32_bf16 v[10:13], v[138:141], v[212:215], v[10:13]
	v_mfma_f32_16x16x32_bf16 v[10:13], v[142:145], v[216:219], v[10:13]
	s_nop 0
	s_nop 0
	v_mfma_f32_16x16x32_bf16 v[54:57], v[146:149], v[164:167], v[54:57]
	v_mfma_f32_16x16x32_bf16 v[54:57], v[150:153], v[182:185], v[54:57]
	v_mfma_f32_16x16x32_bf16 v[50:53], v[154:157], v[164:167], v[50:53]
	v_mfma_f32_16x16x32_bf16 v[50:53], v[160:163], v[182:185], v[50:53]
	v_mfma_f32_16x16x32_bf16 v[38:41], v[146:149], v[186:189], v[38:41]
	v_mfma_f32_16x16x32_bf16 v[38:41], v[150:153], v[190:193], v[38:41]
	v_mfma_f32_16x16x32_bf16 v[34:37], v[154:157], v[186:189], v[34:37]
	v_mfma_f32_16x16x32_bf16 v[34:37], v[160:163], v[190:193], v[34:37]
	v_mfma_f32_16x16x32_bf16 v[22:25], v[146:149], v[194:197], v[22:25]
	v_mfma_f32_16x16x32_bf16 v[22:25], v[150:153], v[198:201], v[22:25]
	v_mfma_f32_16x16x32_bf16 v[18:21], v[154:157], v[194:197], v[18:21]
	v_mfma_f32_16x16x32_bf16 v[18:21], v[160:163], v[198:201], v[18:21]
	v_mfma_f32_16x16x32_bf16 v[6:9], v[146:149], v[212:215], v[6:9]
	v_mfma_f32_16x16x32_bf16 v[6:9], v[150:153], v[216:219], v[6:9]
	v_mfma_f32_16x16x32_bf16 v[2:5], v[154:157], v[212:215], v[2:5]
	v_mfma_f32_16x16x32_bf16 v[2:5], v[160:163], v[216:219], v[2:5]
	s_nop 0
	s_barrier
	s_add_u32 s44, s44, 0x100
	s_addc_u32 s45, s45, 0
	s_add_u32 s52, s52, 0x100
	s_addc_u32 s53, s53, 0
	s_cmp_ge_u32 s54, s14
	s_mov_b32 s48, s54
	s_cbranch_scc0 .LBB0_753
	s_and_b64 vcc, exec, s[20:21]
	s_cbranch_vccz .LBB0_756
	s_barrier

; #define PG8_STAGE(bufoff, gbase, voff) do { _Pragma("unroll") for (int _i = 0; _i < 2; ++_i) \
;         __builtin_amdgcn_global_load_lds((const unsigned*)((const char*)(gbase) + (voff)[_i]), (PG8_LAS unsigned*)(lds + (bufoff) + ldsw + _i * 8192), 16, 0, 0); } while (0)
; #define PG8_LDA(dst, b, h) do { _Pragma("unroll") for (int m = 0; m < 4; ++m) _Pragma("unroll") for (int k = 0; k < 2; ++k) dst[m][k] = *(const PG8_LAS bf16x8*)(lds + PG8_SA(b, h) + aoff + m * 2048 + k * 1024); } while (0)
; #define PG8_LDB(dst, b, h) do { _Pragma("unroll") for (int n = 0; n < 2; ++n) _Pragma("unroll") for (int k = 0; k < 2; ++k) dst[n][k] = *(const PG8_LAS bf16x8*)(lds + PG8_SB(b, h) + boff + n * 2048 + k * 1024); } while (0)
; #define PG8_MMA(ai, bj, At, Bt) do { __builtin_amdgcn_s_setprio(1); _Pragma("unroll") for (int m = 0; m < 4; ++m) _Pragma("unroll") for (int n = 0; n < 2; ++n) _Pragma("unroll") for (int k = 0; k < 2; ++k) \
;         acc[ai][bj][m][n] = __builtin_amdgcn_mfma_f32_16x16x32_bf16(Bt[n][k], At[m][k], acc[ai][bj][m][n], 0, 0, 0); __builtin_amdgcn_s_setprio(0); } while (0)
; #define PG8_WAIT_V(n) asm volatile("s_waitcnt vmcnt(" #n ")" ::: "memory")
; #define PG8_WAIT_L(n) asm volatile("s_waitcnt lgkmcnt(" #n ")" ::: "memory")
; #define PG8_BAR __builtin_amdgcn_s_barrier()
; #define PG8_SCHED __builtin_amdgcn_sched_barrier(0)
; template <class Epi, class Sched, bool ALIGN_EPI = false, bool SP2 = false>
; __device__ __forceinline__ void gemm_phase(PG8_LAS unsigned char* lds, const Gemm g, const Sched& S, const Epi& E, const int wave_s) {
;     ...
;             PG8_LDB(B0, 0, 0); PG8_LDB(B1, 0, 1); PG8_SCHED; PG8_LDA(At, 0, 0); PG8_STAGE(PG8_SA(1, 1), a1 + hstep, voffA);
;             PG8_WAIT_V(8); PG8_WAIT_L(0); PG8_BAR; PG8_MMA(0, 0, At, B0); PG8_MMA(0, 1, At, B1); PG8_BAR; PG8_SCHED;
;             PG8_LDA(At, 0, 1); PG8_STAGE(PG8_SB(0, 0), b2, voffB); PG8_STAGE(PG8_SB(0, 1), b2 + bhstep, voffB); PG8_STAGE(PG8_SA(0, 0), a2, voffA);
;             PG8_WAIT_V(8); PG8_WAIT_L(0); PG8_BAR; PG8_MMA(1, 0, At, B0); PG8_MMA(1, 1, At, B1); PG8_BAR; PG8_SCHED;
.LBB0_843:
	s_add_u32 s44, s42, 0xfffc0080
	s_addc_u32 s45, s43, -1
	s_add_i32 s52, 0, 0x10000
	s_cmp_eq_u32 s51, 12
	s_cselect_b32 s47, s17, s45
	s_cselect_b32 s46, s29, s44
	v_add_u32_e32 v148, s52, v151
	s_cselect_b32 s45, s23, s50
	s_cselect_b32 s44, s48, s49
	s_add_i32 s54, 0, 0x14000
	ds_read_b128 v[144:147], v148
	ds_read_b128 v[160:163], v148 offset:1024
	ds_read_b128 v[164:167], v148 offset:2048
	s_nop 0
	ds_read_b128 v[168:171], v148 offset:3072
	v_add_u32_e32 v148, s54, v151
	ds_read_b128 v[172:175], v148
	ds_read_b128 v[176:179], v148 offset:1024
	ds_read_b128 v[180:183], v148 offset:2048
	ds_read_b128 v[184:187], v148 offset:3072
	v_lshl_add_u64 v[148:149], s[42:43], 0, v[140:141]
	s_add_i32 m0, s7, 0xc000
	ds_read_b128 v[188:191], v155
	ds_read_b128 v[192:195], v155 offset:1024
	ds_read_b128 v[196:199], v155 offset:2048
	ds_read_b128 v[204:207], v155 offset:3072
	ds_read_b128 v[208:211], v155 offset:4096
	ds_read_b128 v[212:215], v155 offset:5120
	ds_read_b128 v[216:219], v155 offset:6144
	ds_read_b128 v[220:223], v155 offset:7168
	global_load_lds_dwordx4 v[148:149], off
	v_lshl_add_u64 v[148:149], s[42:43], 0, v[142:143]
	s_add_i32 m0, s7, 0xe000
	s_nop 0
	global_load_lds_dwordx4 v[148:149], off
	s_waitcnt vmcnt(8)
	s_waitcnt lgkmcnt(0)
	s_barrier
	s_nop 0
	s_waitcnt lgkmcnt(0)
	v_mfma_f32_16x16x32_bf16 v[126:129], v[144:147], v[188:191], v[126:129]
	v_mfma_f32_16x16x32_bf16 v[126:129], v[160:163], v[192:195], v[126:129]
	v_mfma_f32_16x16x32_bf16 v[122:125], v[164:167], v[188:191], v[122:125]
	v_mfma_f32_16x16x32_bf16 v[122:125], v[168:171], v[192:195], v[122:125]
	v_mfma_f32_16x16x32_bf16 v[110:113], v[144:147], v[196:199], v[110:113]
	v_mfma_f32_16x16x32_bf16 v[110:113], v[160:163], v[204:207], v[110:113]
	v_mfma_f32_16x16x32_bf16 v[106:109], v[164:167], v[196:199], v[106:109]
	v_mfma_f32_16x16x32_bf16 v[106:109], v[168:171], v[204:207], v[106:109]
	v_mfma_f32_16x16x32_bf16 v[94:97], v[144:147], v[208:211], v[94:97]
	v_mfma_f32_16x16x32_bf16 v[94:97], v[160:163], v[212:215], v[94:97]
	v_mfma_f32_16x16x32_bf16 v[90:93], v[164:167], v[208:211], v[90:93]
	v_mfma_f32_16x16x32_bf16 v[90:93], v[168:171], v[212:215], v[90:93]
	v_mfma_f32_16x16x32_bf16 v[78:81], v[144:147], v[216:219], v[78:81]
	v_mfma_f32_16x16x32_bf16 v[78:81], v[160:163], v[220:223], v[78:81]
	v_mfma_f32_16x16x32_bf16 v[74:77], v[164:167], v[216:219], v[74:77]
	v_mfma_f32_16x16x32_bf16 v[74:77], v[168:171], v[220:223], v[74:77]
	s_nop 0
	s_nop 0
	v_mfma_f32_16x16x32_bf16 v[118:121], v[172:175], v[188:191], v[118:121]
	v_mfma_f32_16x16x32_bf16 v[118:121], v[176:179], v[192:195], v[118:121]
	v_mfma_f32_16x16x32_bf16 v[114:117], v[180:183], v[188:191], v[114:117]
	v_mfma_f32_16x16x32_bf16 v[114:117], v[184:187], v[192:195], v[114:117]
	v_mfma_f32_16x16x32_bf16 v[102:105], v[172:175], v[196:199], v[102:105]
	v_mfma_f32_16x16x32_bf16 v[102:105], v[176:179], v[204:207], v[102:105]
	v_mfma_f32_16x16x32_bf16 v[98:101], v[180:183], v[196:199], v[98:101]
	v_mfma_f32_16x16x32_bf16 v[98:101], v[184:187], v[204:207], v[98:101]
	v_mfma_f32_16x16x32_bf16 v[86:89], v[172:175], v[208:211], v[86:89]
	v_mfma_f32_16x16x32_bf16 v[86:89], v[176:179], v[212:215], v[86:89]
	v_mfma_f32_16x16x32_bf16 v[82:85], v[180:183], v[208:211], v[82:85]
	v_mfma_f32_16x16x32_bf16 v[82:85], v[184:187], v[212:215], v[82:85]
	v_mfma_f32_16x16x32_bf16 v[70:73], v[172:175], v[216:219], v[70:73]
	v_mfma_f32_16x16x32_bf16 v[70:73], v[176:179], v[220:223], v[70:73]
	v_mfma_f32_16x16x32_bf16 v[66:69], v[180:183], v[216:219], v[66:69]
	v_mfma_f32_16x16x32_bf16 v[66:69], v[184:187], v[220:223], v[66:69]
	s_nop 0
	s_barrier
	s_add_i32 s52, s52, s6
	v_lshl_add_u64 v[148:149], s[44:45], 0, v[134:135]
	s_mov_b32 m0, s52
	ds_read_b128 v[188:191], v155 offset:16384
	ds_read_b128 v[192:195], v155 offset:17408
	ds_read_b128 v[196:199], v155 offset:18432
	ds_read_b128 v[204:207], v155 offset:19456
	ds_read_b128 v[208:211], v155 offset:20480
	ds_read_b128 v[212:215], v155 offset:21504
	ds_read_b128 v[216:219], v155 offset:22528
	ds_read_b128 v[220:223], v155 offset:23552
	global_load_lds_dwordx4 v[148:149], off
	s_add_i32 m0, s52, 0x2000
	s_add_u32 s52, s44, 0x10000
	v_lshl_add_u64 v[200:201], s[44:45], 0, v[138:139]
	s_addc_u32 s53, s45, 0
	s_add_i32 s54, s54, s6
	global_load_lds_dwordx4 v[200:201], off
	v_lshl_add_u64 v[224:225], s[52:53], 0, v[134:135]
	s_mov_b32 m0, s54
	v_lshl_add_u64 v[226:227], s[46:47], 0, v[136:137]
	global_load_lds_dwordx4 v[224:225], off
	v_lshl_add_u64 v[224:225], s[52:53], 0, v[138:139]
	s_add_i32 m0, s54, 0x2000
	s_nop 0
	global_load_lds_dwordx4 v[224:225], off
	v_lshl_add_u64 v[224:225], s[46:47], 0, v[132:133]
	s_mov_b32 m0, s7
	s_nop 0
	global_load_lds_dwordx4 v[224:225], off
	s_mov_b32 m0, s8
	s_nop 0
	global_load_lds_dwordx4 v[226:227], off
	s_waitcnt vmcnt(8)
	s_waitcnt lgkmcnt(0)
	s_barrier
; #define PG8_STAGE(bufoff, gbase, voff) do { _Pragma("unroll") for (int _i = 0; _i < 2; ++_i) \
;         __builtin_amdgcn_global_load_lds((const unsigned*)((const char*)(gbase) + (voff)[_i]), (PG8_LAS unsigned*)(lds + (bufoff) + ldsw + _i * 8192), 16, 0, 0); } while (0)
; #define PG8_LDA(dst, b, h) do { _Pragma("unroll") for (int m = 0; m < 4; ++m) _Pragma("unroll") for (int k = 0; k < 2; ++k) dst[m][k] = *(const PG8_LAS bf16x8*)(lds + PG8_SA(b, h) + aoff + m * 2048 + k * 1024); } while (0)
; #define PG8_LDB(dst, b, h) do { _Pragma("unroll") for (int n = 0; n < 2; ++n) _Pragma("unroll") for (int k = 0; k < 2; ++k) dst[n][k] = *(const PG8_LAS bf16x8*)(lds + PG8_SB(b, h) + boff + n * 2048 + k * 1024); } while (0)
; #define PG8_MMA(ai, bj, At, Bt) do { __builtin_amdgcn_s_setprio(1); _Pragma("unroll") for (int m = 0; m < 4; ++m) _Pragma("unroll") for (int n = 0; n < 2; ++n) _Pragma("unroll") for (int k = 0; k < 2; ++k) \
;         acc[ai][bj][m][n] = __builtin_amdgcn_mfma_f32_16x16x32_bf16(Bt[n][k], At[m][k], acc[ai][bj][m][n], 0, 0, 0); __builtin_amdgcn_s_setprio(0); } while (0)
; #define PG8_BAR __builtin_amdgcn_s_barrier()
; template <class Epi, class Sched, bool ALIGN_EPI = false, bool SP2 = false>
; __device__ __forceinline__ void gemm_phase(PG8_LAS unsigned char* lds, const Gemm g, const Sched& S, const Epi& E, const int wave_s) {
;     ...
;             PG8_LDB(B0, 0, 0); PG8_LDB(B1, 0, 1); PG8_SCHED; PG8_LDA(At, 0, 0); PG8_STAGE(PG8_SA(1, 1), a1 + hstep, voffA);
;             PG8_WAIT_V(8); PG8_WAIT_L(0); PG8_BAR; PG8_MMA(0, 0, At, B0); PG8_MMA(0, 1, At, B1); PG8_BAR; PG8_SCHED;
;             PG8_LDA(At, 0, 1); PG8_STAGE(PG8_SB(0, 0), b2, voffB); PG8_STAGE(PG8_SB(0, 1), b2 + bhstep, voffB); PG8_STAGE(PG8_SA(0, 0), a2, voffA);
;             PG8_WAIT_V(8); PG8_WAIT_L(0); PG8_BAR; PG8_MMA(1, 0, At, B0); PG8_MMA(1, 1, At, B1); PG8_BAR; PG8_SCHED;
;             PG8_LDB(B0, 1, 0); PG8_LDB(B1, 1, 1); PG8_SCHED; PG8_LDA(At, 1, 0); PG8_STAGE(PG8_SA(0, 1), a2 + hstep, voffA);
;             PG8_WAIT_V(8); PG8_WAIT_L(0); PG8_BAR; PG8_MMA(0, 0, At, B0); PG8_MMA(0, 1, At, B1); PG8_BAR; PG8_SCHED;
;             PG8_LDA(At, 1, 1); PG8_STAGE(PG8_SB(1, 0), b3, voffB); PG8_STAGE(PG8_SB(1, 1), b3 + bhstep, voffB); PG8_STAGE(PG8_SA(1, 0), a3, voffA);
;             PG8_WAIT_V(8); PG8_WAIT_L(0); PG8_BAR; PG8_MMA(1, 0, At, B0); PG8_MMA(1, 1, At, B1); PG8_BAR; PG8_SCHED;
	s_nop 0
	s_waitcnt lgkmcnt(0)
	v_mfma_f32_16x16x32_bf16 v[62:65], v[144:147], v[188:191], v[62:65]
	v_mfma_f32_16x16x32_bf16 v[62:65], v[160:163], v[192:195], v[62:65]
	v_mfma_f32_16x16x32_bf16 v[58:61], v[164:167], v[188:191], v[58:61]
	v_mfma_f32_16x16x32_bf16 v[58:61], v[168:171], v[192:195], v[58:61]
	v_mfma_f32_16x16x32_bf16 v[46:49], v[144:147], v[196:199], v[46:49]
	v_mfma_f32_16x16x32_bf16 v[46:49], v[160:163], v[204:207], v[46:49]
	v_mfma_f32_16x16x32_bf16 v[42:45], v[164:167], v[196:199], v[42:45]
	v_mfma_f32_16x16x32_bf16 v[42:45], v[168:171], v[204:207], v[42:45]
	v_mfma_f32_16x16x32_bf16 v[30:33], v[144:147], v[208:211], v[30:33]
	v_mfma_f32_16x16x32_bf16 v[30:33], v[160:163], v[212:215], v[30:33]
	v_mfma_f32_16x16x32_bf16 v[26:29], v[164:167], v[208:211], v[26:29]
	v_mfma_f32_16x16x32_bf16 v[26:29], v[168:171], v[212:215], v[26:29]
	v_mfma_f32_16x16x32_bf16 v[14:17], v[144:147], v[216:219], v[14:17]
	v_mfma_f32_16x16x32_bf16 v[14:17], v[160:163], v[220:223], v[14:17]
	v_mfma_f32_16x16x32_bf16 v[10:13], v[164:167], v[216:219], v[10:13]
	v_mfma_f32_16x16x32_bf16 v[10:13], v[168:171], v[220:223], v[10:13]
	s_nop 0
	s_nop 0
	v_mfma_f32_16x16x32_bf16 v[54:57], v[172:175], v[188:191], v[54:57]
	v_mfma_f32_16x16x32_bf16 v[54:57], v[176:179], v[192:195], v[54:57]
	v_mfma_f32_16x16x32_bf16 v[50:53], v[180:183], v[188:191], v[50:53]
	v_mfma_f32_16x16x32_bf16 v[50:53], v[184:187], v[192:195], v[50:53]
	v_mfma_f32_16x16x32_bf16 v[38:41], v[172:175], v[196:199], v[38:41]
	v_mfma_f32_16x16x32_bf16 v[38:41], v[176:179], v[204:207], v[38:41]
	v_mfma_f32_16x16x32_bf16 v[34:37], v[180:183], v[196:199], v[34:37]
	v_mfma_f32_16x16x32_bf16 v[34:37], v[184:187], v[204:207], v[34:37]
	v_mfma_f32_16x16x32_bf16 v[22:25], v[172:175], v[208:211], v[22:25]
	v_mfma_f32_16x16x32_bf16 v[22:25], v[176:179], v[212:215], v[22:25]
	v_mfma_f32_16x16x32_bf16 v[18:21], v[180:183], v[208:211], v[18:21]
	v_mfma_f32_16x16x32_bf16 v[18:21], v[184:187], v[212:215], v[18:21]
	v_mfma_f32_16x16x32_bf16 v[6:9], v[172:175], v[216:219], v[6:9]
	v_mfma_f32_16x16x32_bf16 v[6:9], v[176:179], v[220:223], v[6:9]
	v_mfma_f32_16x16x32_bf16 v[2:5], v[180:183], v[216:219], v[2:5]
	v_mfma_f32_16x16x32_bf16 v[2:5], v[184:187], v[220:223], v[2:5]
	s_nop 0
	s_barrier
	s_add_i32 s52, 0, 0x18000
	v_add_u32_e32 v159, s52, v151
	s_add_i32 s53, 0, 0x1c000
	ds_read_b128 v[144:147], v159
	ds_read_b128 v[160:163], v159 offset:1024
	ds_read_b128 v[164:167], v159 offset:2048
	ds_read_b128 v[168:171], v159 offset:3072
	v_add_u32_e32 v159, s53, v151
	ds_read_b128 v[172:175], v159
	ds_read_b128 v[176:179], v159 offset:1024
	ds_read_b128 v[180:183], v159 offset:2048
	ds_read_b128 v[184:187], v159 offset:3072
	s_add_u32 s46, s46, 0x40000
	s_addc_u32 s47, s47, 0
	s_mov_b32 m0, s9
	v_lshl_add_u64 v[228:229], s[46:47], 0, v[132:133]
	ds_read_b128 v[188:191], v155 offset:32768
	ds_read_b128 v[192:195], v155 offset:33792
	ds_read_b128 v[196:199], v155 offset:34816
	ds_read_b128 v[204:207], v155 offset:35840
	ds_read_b128 v[208:211], v155 offset:36864
	ds_read_b128 v[212:215], v155 offset:37888
	ds_read_b128 v[216:219], v155 offset:38912
	ds_read_b128 v[220:223], v155 offset:39936
	global_load_lds_dwordx4 v[228:229], off
	v_lshl_add_u64 v[228:229], s[46:47], 0, v[136:137]
	s_mov_b32 m0, s10
	s_nop 0
	global_load_lds_dwordx4 v[228:229], off
	s_waitcnt vmcnt(8)
	s_waitcnt lgkmcnt(0)
	s_barrier
	s_nop 0
	s_waitcnt lgkmcnt(0)
	v_mfma_f32_16x16x32_bf16 v[126:129], v[144:147], v[188:191], v[126:129]
	v_mfma_f32_16x16x32_bf16 v[126:129], v[160:163], v[192:195], v[126:129]
	v_mfma_f32_16x16x32_bf16 v[122:125], v[164:167], v[188:191], v[122:125]
	v_mfma_f32_16x16x32_bf16 v[122:125], v[168:171], v[192:195], v[122:125]
	v_mfma_f32_16x16x32_bf16 v[110:113], v[144:147], v[196:199], v[110:113]
	v_mfma_f32_16x16x32_bf16 v[110:113], v[160:163], v[204:207], v[110:113]
	v_mfma_f32_16x16x32_bf16 v[106:109], v[164:167], v[196:199], v[106:109]
	v_mfma_f32_16x16x32_bf16 v[106:109], v[168:171], v[204:207], v[106:109]
	v_mfma_f32_16x16x32_bf16 v[94:97], v[144:147], v[208:211], v[94:97]
	v_mfma_f32_16x16x32_bf16 v[94:97], v[160:163], v[212:215], v[94:97]
	v_mfma_f32_16x16x32_bf16 v[90:93], v[164:167], v[208:211], v[90:93]
	v_mfma_f32_16x16x32_bf16 v[90:93], v[168:171], v[212:215], v[90:93]
	v_mfma_f32_16x16x32_bf16 v[78:81], v[144:147], v[216:219], v[78:81]
	v_mfma_f32_16x16x32_bf16 v[78:81], v[160:163], v[220:223], v[78:81]
	v_mfma_f32_16x16x32_bf16 v[74:77], v[164:167], v[216:219], v[74:77]
	v_mfma_f32_16x16x32_bf16 v[74:77], v[168:171], v[220:223], v[74:77]
	s_nop 0
	s_nop 0
	v_mfma_f32_16x16x32_bf16 v[118:121], v[172:175], v[188:191], v[118:121]
	v_mfma_f32_16x16x32_bf16 v[118:121], v[176:179], v[192:195], v[118:121]
	v_mfma_f32_16x16x32_bf16 v[114:117], v[180:183], v[188:191], v[114:117]
	v_mfma_f32_16x16x32_bf16 v[114:117], v[184:187], v[192:195], v[114:117]
	v_mfma_f32_16x16x32_bf16 v[102:105], v[172:175], v[196:199], v[102:105]
	v_mfma_f32_16x16x32_bf16 v[102:105], v[176:179], v[204:207], v[102:105]
	v_mfma_f32_16x16x32_bf16 v[98:101], v[180:183], v[196:199], v[98:101]
	v_mfma_f32_16x16x32_bf16 v[98:101], v[184:187], v[204:207], v[98:101]
	v_mfma_f32_16x16x32_bf16 v[86:89], v[172:175], v[208:211], v[86:89]
	v_mfma_f32_16x16x32_bf16 v[86:89], v[176:179], v[212:215], v[86:89]
	v_mfma_f32_16x16x32_bf16 v[82:85], v[180:183], v[208:211], v[82:85]
	v_mfma_f32_16x16x32_bf16 v[82:85], v[184:187], v[212:215], v[82:85]
	v_mfma_f32_16x16x32_bf16 v[70:73], v[172:175], v[216:219], v[70:73]
	v_mfma_f32_16x16x32_bf16 v[70:73], v[176:179], v[220:223], v[70:73]
	v_mfma_f32_16x16x32_bf16 v[66:69], v[180:183], v[216:219], v[66:69]
	v_mfma_f32_16x16x32_bf16 v[66:69], v[184:187], v[220:223], v[66:69]
	s_nop 0
	s_barrier
; #define PG8_STAGE(bufoff, gbase, voff) do { _Pragma("unroll") for (int _i = 0; _i < 2; ++_i) \
;         __builtin_amdgcn_global_load_lds((const unsigned*)((const char*)(gbase) + (voff)[_i]), (PG8_LAS unsigned*)(lds + (bufoff) + ldsw + _i * 8192), 16, 0, 0); } while (0)
; #define PG8_LDA(dst, b, h) do { _Pragma("unroll") for (int m = 0; m < 4; ++m) _Pragma("unroll") for (int k = 0; k < 2; ++k) dst[m][k] = *(const PG8_LAS bf16x8*)(lds + PG8_SA(b, h) + aoff + m * 2048 + k * 1024); } while (0)
; #define PG8_BAR __builtin_amdgcn_s_barrier()
; template <class Epi, class Sched, bool ALIGN_EPI = false, bool SP2 = false>
; __device__ __forceinline__ void gemm_phase(PG8_LAS unsigned char* lds, const Gemm g, const Sched& S, const Epi& E, const int wave_s) {
;     ...
;             PG8_LDA(At, 1, 1); PG8_STAGE(PG8_SB(1, 0), b3, voffB); PG8_STAGE(PG8_SB(1, 1), b3 + bhstep, voffB); PG8_STAGE(PG8_SA(1, 0), a3, voffA);
;             PG8_WAIT_V(8); PG8_WAIT_L(0); PG8_BAR; PG8_MMA(1, 0, At, B0); PG8_MMA(1, 1, At, B1); PG8_BAR; PG8_SCHED;
;             } else {
;             PG8_LDB(B0, 0, 0); PG8_SCHED; PG8_LDA(At, 0, 0); PG8_STAGE(PG8_SA(1, 1), a1 + hstep, voffA);
;             PG8_WAIT_L(8); PG8_BAR; PG8_WAIT_L(0); PG8_MMA(0, 0, At, B0); PG8_BAR; PG8_SCHED;
;             PG8_LDB(B1, 0, 1); PG8_STAGE(PG8_SB(0, 0), b2, voffB);
;             PG8_BAR; PG8_WAIT_L(0); PG8_MMA(0, 1, At, B1); PG8_BAR;
;             PG8_LDA(At, 0, 1); PG8_STAGE(PG8_SA(0, 0), a2, voffA);
;             PG8_BAR; PG8_WAIT_L(0); PG8_MMA(1, 0, At, B0); PG8_BAR; PG8_SCHED;
;             PG8_STAGE(PG8_SB(0, 1), b2 + bhstep, voffB);
;             PG8_WAIT_V(6); PG8_BAR; PG8_MMA(1, 1, At, B1); PG8_BAR;
;             PG8_LDB(B0, 1, 0); PG8_SCHED; PG8_LDA(At, 1, 0); PG8_STAGE(PG8_SA(0, 1), a2 + hstep, voffA);
;             PG8_WAIT_L(8); PG8_BAR; PG8_WAIT_L(0); PG8_MMA(0, 0, At, B0); PG8_BAR; PG8_SCHED;
;             PG8_LDB(B1, 1, 1); PG8_STAGE(PG8_SB(1, 0), b3, voffB);
;             PG8_BAR; PG8_WAIT_L(0); PG8_MMA(0, 1, At, B1); PG8_BAR;
;             PG8_LDA(At, 1, 1); PG8_STAGE(PG8_SA(1, 0), a3, voffA);
;             PG8_BAR; PG8_WAIT_L(0); PG8_MMA(1, 0, At, B0); PG8_BAR; PG8_SCHED;
;             PG8_STAGE(PG8_SB(1, 1), b3 + bhstep, voffB);
;             PG8_WAIT_V(6); PG8_BAR; PG8_MMA(1, 1, At, B1); PG8_BAR;
;             }
;         }
;         if constexpr (ALIGN_EPI) { if (wr == 0) PG8_BAR; }
	s_add_i32 s46, s52, s6
	v_lshl_add_u64 v[148:149], v[148:149], 0, s[24:25]
	s_mov_b32 m0, s46
	ds_read_b128 v[188:191], v155 offset:49152
	ds_read_b128 v[192:195], v155 offset:50176
	ds_read_b128 v[196:199], v155 offset:51200
	ds_read_b128 v[204:207], v155 offset:52224
	ds_read_b128 v[208:211], v155 offset:53248
	ds_read_b128 v[212:215], v155 offset:54272
	ds_read_b128 v[216:219], v155 offset:55296
	ds_read_b128 v[220:223], v155 offset:56320
	global_load_lds_dwordx4 v[148:149], off
	s_add_i32 m0, s46, 0x2000
	s_add_u32 s44, s44, 0x10080
	v_lshl_add_u64 v[148:149], v[200:201], 0, s[24:25]
	s_addc_u32 s45, s45, 0
	s_add_i32 s46, s53, s6
	global_load_lds_dwordx4 v[148:149], off
	v_lshl_add_u64 v[148:149], s[44:45], 0, v[134:135]
	s_mov_b32 m0, s46
	s_nop 0
	global_load_lds_dwordx4 v[148:149], off
	v_lshl_add_u64 v[148:149], s[44:45], 0, v[138:139]
	s_add_i32 m0, s46, 0x2000
	s_nop 0
	global_load_lds_dwordx4 v[148:149], off
	v_lshl_add_u64 v[148:149], v[224:225], 0, s[24:25]
	s_mov_b32 m0, s11
	s_nop 0
	global_load_lds_dwordx4 v[148:149], off
	v_lshl_add_u64 v[148:149], v[226:227], 0, s[24:25]
	s_mov_b32 m0, s12
	s_nop 0
	global_load_lds_dwordx4 v[148:149], off
	s_waitcnt vmcnt(8)
	s_waitcnt lgkmcnt(0)
	s_barrier
	s_nop 0
	s_waitcnt lgkmcnt(0)
	v_mfma_f32_16x16x32_bf16 v[62:65], v[144:147], v[188:191], v[62:65]
	v_mfma_f32_16x16x32_bf16 v[62:65], v[160:163], v[192:195], v[62:65]
	v_mfma_f32_16x16x32_bf16 v[58:61], v[164:167], v[188:191], v[58:61]
	v_mfma_f32_16x16x32_bf16 v[58:61], v[168:171], v[192:195], v[58:61]
	v_mfma_f32_16x16x32_bf16 v[46:49], v[144:147], v[196:199], v[46:49]
	v_mfma_f32_16x16x32_bf16 v[46:49], v[160:163], v[204:207], v[46:49]
	v_mfma_f32_16x16x32_bf16 v[42:45], v[164:167], v[196:199], v[42:45]
	v_mfma_f32_16x16x32_bf16 v[42:45], v[168:171], v[204:207], v[42:45]
	v_mfma_f32_16x16x32_bf16 v[30:33], v[144:147], v[208:211], v[30:33]
	v_mfma_f32_16x16x32_bf16 v[30:33], v[160:163], v[212:215], v[30:33]
	v_mfma_f32_16x16x32_bf16 v[26:29], v[164:167], v[208:211], v[26:29]
	v_mfma_f32_16x16x32_bf16 v[26:29], v[168:171], v[212:215], v[26:29]
	v_mfma_f32_16x16x32_bf16 v[14:17], v[144:147], v[216:219], v[14:17]
	v_mfma_f32_16x16x32_bf16 v[14:17], v[160:163], v[220:223], v[14:17]
	v_mfma_f32_16x16x32_bf16 v[10:13], v[164:167], v[216:219], v[10:13]
	v_mfma_f32_16x16x32_bf16 v[10:13], v[168:171], v[220:223], v[10:13]
	s_nop 0
	s_nop 0
	v_mfma_f32_16x16x32_bf16 v[54:57], v[172:175], v[188:191], v[54:57]
	v_mfma_f32_16x16x32_bf16 v[54:57], v[176:179], v[192:195], v[54:57]
	v_mfma_f32_16x16x32_bf16 v[50:53], v[180:183], v[188:191], v[50:53]
	v_mfma_f32_16x16x32_bf16 v[50:53], v[184:187], v[192:195], v[50:53]
	v_mfma_f32_16x16x32_bf16 v[38:41], v[172:175], v[196:199], v[38:41]
	v_mfma_f32_16x16x32_bf16 v[38:41], v[176:179], v[204:207], v[38:41]
	v_mfma_f32_16x16x32_bf16 v[34:37], v[180:183], v[196:199], v[34:37]
	v_mfma_f32_16x16x32_bf16 v[34:37], v[184:187], v[204:207], v[34:37]
	v_mfma_f32_16x16x32_bf16 v[22:25], v[172:175], v[208:211], v[22:25]
	v_mfma_f32_16x16x32_bf16 v[22:25], v[176:179], v[212:215], v[22:25]
	v_mfma_f32_16x16x32_bf16 v[18:21], v[180:183], v[208:211], v[18:21]
	v_mfma_f32_16x16x32_bf16 v[18:21], v[184:187], v[212:215], v[18:21]
	v_mfma_f32_16x16x32_bf16 v[6:9], v[172:175], v[216:219], v[6:9]
	v_mfma_f32_16x16x32_bf16 v[6:9], v[176:179], v[220:223], v[6:9]
	v_mfma_f32_16x16x32_bf16 v[2:5], v[180:183], v[216:219], v[2:5]
	v_mfma_f32_16x16x32_bf16 v[2:5], v[184:187], v[220:223], v[2:5]
	s_nop 0
	s_barrier
	s_add_i32 s51, s51, 2
	s_add_u32 s42, s42, 0x100
	s_addc_u32 s43, s43, 0
	s_add_u32 s49, s49, 0x100
	s_addc_u32 s50, s50, 0
	s_cmp_gt_u32 s51, 13
	s_cbranch_scc0 .LBB0_843
	s_and_b64 vcc, exec, s[20:21]
	s_cbranch_vccz .LBB0_846
	s_barrier

; #define PG8_STAGE(bufoff, gbase, voff) do { _Pragma("unroll") for (int _i = 0; _i < 2; ++_i) \
;         __builtin_amdgcn_global_load_lds((const unsigned*)((const char*)(gbase) + (voff)[_i]), (PG8_LAS unsigned*)(lds + (bufoff) + ldsw + _i * 8192), 16, 0, 0); } while (0)
; #define PG8_LDA(dst, b, h) do { _Pragma("unroll") for (int m = 0; m < 4; ++m) _Pragma("unroll") for (int k = 0; k < 2; ++k) dst[m][k] = *(const PG8_LAS bf16x8*)(lds + PG8_SA(b, h) + aoff + m * 2048 + k * 1024); } while (0)
; #define PG8_LDB(dst, b, h) do { _Pragma("unroll") for (int n = 0; n < 2; ++n) _Pragma("unroll") for (int k = 0; k < 2; ++k) dst[n][k] = *(const PG8_LAS bf16x8*)(lds + PG8_SB(b, h) + boff + n * 2048 + k * 1024); } while (0)
; #define PG8_WAIT_V(n) asm volatile("s_waitcnt vmcnt(" #n ")" ::: "memory")
; #define PG8_WAIT_L(n) asm volatile("s_waitcnt lgkmcnt(" #n ")" ::: "memory")
; #define PG8_BAR __builtin_amdgcn_s_barrier()
; #define PG8_SCHED __builtin_amdgcn_sched_barrier(0)
; template <class Epi, class Sched, bool ALIGN_EPI = false, bool SP2 = false>
; __device__ __forceinline__ void gemm_phase(PG8_LAS unsigned char* lds, const Gemm g, const Sched& S, const Epi& E, const int wave_s) {
;     ...
;         const char* nA = has_next ? (const char*)g.A + (size_t)nxt.pm * tstep : cA; const char* nB = has_next ? (const char*)g.Bt + (size_t)nxt.pn * tstep : cB;
;         for (int t = 0; t < nt; t += 2) {
;             const bool last = (t == nt - 2);
;             const char* a1 = cA + (size_t)(t + 1) * kstep;
;             const char* a2 = last ? nA : cA + (size_t)(t + 2) * kstep; const char* b2 = last ? nB : cB + (size_t)(t + 2) * kstep;
;             const char* a3 = a2 + kstep; const char* b3 = b2 + kstep;
;             if (last && has_next) S.a_ready(nxt);
;             if constexpr (SP2) {
;             PG8_LDB(B0, 0, 0); PG8_LDB(B1, 0, 1); PG8_SCHED; PG8_LDA(At, 0, 0); PG8_STAGE(PG8_SA(1, 1), a1 + hstep, voffA);
;             PG8_WAIT_V(8); PG8_WAIT_L(0); PG8_BAR; PG8_MMA(0, 0, At, B0); PG8_MMA(0, 1, At, B1); PG8_BAR; PG8_SCHED;
;             PG8_LDA(At, 0, 1); PG8_STAGE(PG8_SB(0, 0), b2, voffB); PG8_STAGE(PG8_SB(0, 1), b2 + bhstep, voffB); PG8_STAGE(PG8_SA(0, 0), a2, voffA);
;             PG8_WAIT_V(8); PG8_WAIT_L(0); PG8_BAR; PG8_MMA(1, 0, At, B0); PG8_MMA(1, 1, At, B1); PG8_BAR; PG8_SCHED;
.LBB0_923:
	s_add_u32 s46, s42, 0xfff00080
	s_addc_u32 s47, s43, -1
	s_add_i32 s51, 0, 0x10000
	s_cmp_eq_u32 s50, 60
	s_cselect_b32 s49, s15, s47
	s_cselect_b32 s48, s16, s46
	s_cselect_b32 s47, s17, s45
	s_cselect_b32 s46, s23, s29
	s_add_i32 s54, 0, 0x14000
	v_add_u32_e32 v142, s51, v205
	v_add_u32_e32 v160, s54, v205
	ds_read_b128 v[130:133], v142
	ds_read_b128 v[134:137], v142 offset:1024
	ds_read_b128 v[138:141], v142 offset:2048
	ds_read_b128 v[142:145], v142 offset:3072
	ds_read_b128 v[146:149], v160
	ds_read_b128 v[150:153], v160 offset:1024
	ds_read_b128 v[154:157], v160 offset:2048
	ds_read_b128 v[160:163], v160 offset:3072
	v_lshl_add_u64 v[220:221], s[42:43], 0, v[178:179]
	s_add_i32 m0, s5, 0xc000
	ds_read_b128 v[164:167], v208
	ds_read_b128 v[182:185], v208 offset:1024
	ds_read_b128 v[186:189], v208 offset:2048
	ds_read_b128 v[190:193], v208 offset:3072
	ds_read_b128 v[194:197], v208 offset:4096
	ds_read_b128 v[198:201], v208 offset:5120
	ds_read_b128 v[212:215], v208 offset:6144
	ds_read_b128 v[216:219], v208 offset:7168
	global_load_lds_dwordx4 v[220:221], off
	v_lshl_add_u64 v[220:221], s[42:43], 0, v[180:181]
	s_add_i32 m0, s5, 0xe000
	s_nop 0
	global_load_lds_dwordx4 v[220:221], off
	s_waitcnt vmcnt(8)
	s_waitcnt lgkmcnt(0)
	s_barrier
	s_nop 0
	s_waitcnt lgkmcnt(0)
	v_mfma_f32_16x16x32_bf16 v[126:129], v[130:133], v[164:167], v[126:129]
	v_mfma_f32_16x16x32_bf16 v[126:129], v[134:137], v[182:185], v[126:129]
	v_mfma_f32_16x16x32_bf16 v[122:125], v[138:141], v[164:167], v[122:125]
	v_mfma_f32_16x16x32_bf16 v[122:125], v[142:145], v[182:185], v[122:125]
	v_mfma_f32_16x16x32_bf16 v[110:113], v[130:133], v[186:189], v[110:113]
	v_mfma_f32_16x16x32_bf16 v[110:113], v[134:137], v[190:193], v[110:113]
	v_mfma_f32_16x16x32_bf16 v[106:109], v[138:141], v[186:189], v[106:109]
	v_mfma_f32_16x16x32_bf16 v[106:109], v[142:145], v[190:193], v[106:109]
	v_mfma_f32_16x16x32_bf16 v[94:97], v[130:133], v[194:197], v[94:97]
	v_mfma_f32_16x16x32_bf16 v[94:97], v[134:137], v[198:201], v[94:97]
	v_mfma_f32_16x16x32_bf16 v[90:93], v[138:141], v[194:197], v[90:93]
	v_mfma_f32_16x16x32_bf16 v[90:93], v[142:145], v[198:201], v[90:93]
	v_mfma_f32_16x16x32_bf16 v[78:81], v[130:133], v[212:215], v[78:81]
	v_mfma_f32_16x16x32_bf16 v[78:81], v[134:137], v[216:219], v[78:81]
	v_mfma_f32_16x16x32_bf16 v[74:77], v[138:141], v[212:215], v[74:77]
	v_mfma_f32_16x16x32_bf16 v[74:77], v[142:145], v[216:219], v[74:77]
	s_nop 0
	s_nop 0
	v_mfma_f32_16x16x32_bf16 v[118:121], v[146:149], v[164:167], v[118:121]
	v_mfma_f32_16x16x32_bf16 v[118:121], v[150:153], v[182:185], v[118:121]
	v_mfma_f32_16x16x32_bf16 v[114:117], v[154:157], v[164:167], v[114:117]
	v_mfma_f32_16x16x32_bf16 v[114:117], v[160:163], v[182:185], v[114:117]
	v_mfma_f32_16x16x32_bf16 v[102:105], v[146:149], v[186:189], v[102:105]
	v_mfma_f32_16x16x32_bf16 v[102:105], v[150:153], v[190:193], v[102:105]
	v_mfma_f32_16x16x32_bf16 v[98:101], v[154:157], v[186:189], v[98:101]
	v_mfma_f32_16x16x32_bf16 v[98:101], v[160:163], v[190:193], v[98:101]
	v_mfma_f32_16x16x32_bf16 v[86:89], v[146:149], v[194:197], v[86:89]
	v_mfma_f32_16x16x32_bf16 v[86:89], v[150:153], v[198:201], v[86:89]
	v_mfma_f32_16x16x32_bf16 v[82:85], v[154:157], v[194:197], v[82:85]
	v_mfma_f32_16x16x32_bf16 v[82:85], v[160:163], v[198:201], v[82:85]
	v_mfma_f32_16x16x32_bf16 v[70:73], v[146:149], v[212:215], v[70:73]
	v_mfma_f32_16x16x32_bf16 v[70:73], v[150:153], v[216:219], v[70:73]
	v_mfma_f32_16x16x32_bf16 v[66:69], v[154:157], v[212:215], v[66:69]
	v_mfma_f32_16x16x32_bf16 v[66:69], v[160:163], v[216:219], v[66:69]
	s_nop 0
	s_barrier
	s_add_i32 s51, s51, s4
	v_lshl_add_u64 v[220:221], s[46:47], 0, v[170:171]
	s_mov_b32 m0, s51
	ds_read_b128 v[164:167], v208 offset:16384
	ds_read_b128 v[182:185], v208 offset:17408
	ds_read_b128 v[186:189], v208 offset:18432
	ds_read_b128 v[190:193], v208 offset:19456
	ds_read_b128 v[194:197], v208 offset:20480
	ds_read_b128 v[198:201], v208 offset:21504
	ds_read_b128 v[212:215], v208 offset:22528
	ds_read_b128 v[216:219], v208 offset:23552
	global_load_lds_dwordx4 v[220:221], off
	s_add_i32 m0, s51, 0x2000
	s_add_u32 s52, s46, 0x40000
	v_lshl_add_u64 v[222:223], s[46:47], 0, v[158:159]
	s_addc_u32 s53, s47, 0
	s_add_i32 s51, s54, s4
	global_load_lds_dwordx4 v[222:223], off
	v_lshl_add_u64 v[224:225], s[52:53], 0, v[170:171]
	s_mov_b32 m0, s51
	v_lshl_add_u64 v[226:227], s[48:49], 0, v[168:169]
	global_load_lds_dwordx4 v[224:225], off
	v_lshl_add_u64 v[224:225], s[52:53], 0, v[158:159]
	s_add_i32 m0, s51, 0x2000
	s_nop 0
	global_load_lds_dwordx4 v[224:225], off
	v_lshl_add_u64 v[224:225], s[48:49], 0, v[172:173]
	s_mov_b32 m0, s5
	s_nop 0
	global_load_lds_dwordx4 v[224:225], off
	s_mov_b32 m0, s6
	s_nop 0
	global_load_lds_dwordx4 v[226:227], off
	s_waitcnt vmcnt(8)
	s_waitcnt lgkmcnt(0)
	s_barrier
; #define PG8_STAGE(bufoff, gbase, voff) do { _Pragma("unroll") for (int _i = 0; _i < 2; ++_i) \
;         __builtin_amdgcn_global_load_lds((const unsigned*)((const char*)(gbase) + (voff)[_i]), (PG8_LAS unsigned*)(lds + (bufoff) + ldsw + _i * 8192), 16, 0, 0); } while (0)
; #define PG8_LDA(dst, b, h) do { _Pragma("unroll") for (int m = 0; m < 4; ++m) _Pragma("unroll") for (int k = 0; k < 2; ++k) dst[m][k] = *(const PG8_LAS bf16x8*)(lds + PG8_SA(b, h) + aoff + m * 2048 + k * 1024); } while (0)
; #define PG8_LDB(dst, b, h) do { _Pragma("unroll") for (int n = 0; n < 2; ++n) _Pragma("unroll") for (int k = 0; k < 2; ++k) dst[n][k] = *(const PG8_LAS bf16x8*)(lds + PG8_SB(b, h) + boff + n * 2048 + k * 1024); } while (0)
; #define PG8_MMA(ai, bj, At, Bt) do { __builtin_amdgcn_s_setprio(1); _Pragma("unroll") for (int m = 0; m < 4; ++m) _Pragma("unroll") for (int n = 0; n < 2; ++n) _Pragma("unroll") for (int k = 0; k < 2; ++k) \
;         acc[ai][bj][m][n] = __builtin_amdgcn_mfma_f32_16x16x32_bf16(Bt[n][k], At[m][k], acc[ai][bj][m][n], 0, 0, 0); __builtin_amdgcn_s_setprio(0); } while (0)
; #define PG8_WAIT_V(n) asm volatile("s_waitcnt vmcnt(" #n ")" ::: "memory")
; #define PG8_WAIT_L(n) asm volatile("s_waitcnt lgkmcnt(" #n ")" ::: "memory")
; #define PG8_BAR __builtin_amdgcn_s_barrier()
; #define PG8_SCHED __builtin_amdgcn_sched_barrier(0)
; template <class Epi, class Sched, bool ALIGN_EPI = false, bool SP2 = false>
; __device__ __forceinline__ void gemm_phase(PG8_LAS unsigned char* lds, const Gemm g, const Sched& S, const Epi& E, const int wave_s) {
;     ...
;             PG8_WAIT_V(8); PG8_WAIT_L(0); PG8_BAR; PG8_MMA(1, 0, At, B0); PG8_MMA(1, 1, At, B1); PG8_BAR; PG8_SCHED;
;             PG8_LDB(B0, 1, 0); PG8_LDB(B1, 1, 1); PG8_SCHED; PG8_LDA(At, 1, 0); PG8_STAGE(PG8_SA(0, 1), a2 + hstep, voffA);
;             PG8_WAIT_V(8); PG8_WAIT_L(0); PG8_BAR; PG8_MMA(0, 0, At, B0); PG8_MMA(0, 1, At, B1); PG8_BAR; PG8_SCHED;
	s_nop 0
	s_waitcnt lgkmcnt(0)
	v_mfma_f32_16x16x32_bf16 v[62:65], v[130:133], v[164:167], v[62:65]
	v_mfma_f32_16x16x32_bf16 v[62:65], v[134:137], v[182:185], v[62:65]
	v_mfma_f32_16x16x32_bf16 v[58:61], v[138:141], v[164:167], v[58:61]
	v_mfma_f32_16x16x32_bf16 v[58:61], v[142:145], v[182:185], v[58:61]
	v_mfma_f32_16x16x32_bf16 v[46:49], v[130:133], v[186:189], v[46:49]
	v_mfma_f32_16x16x32_bf16 v[46:49], v[134:137], v[190:193], v[46:49]
	v_mfma_f32_16x16x32_bf16 v[42:45], v[138:141], v[186:189], v[42:45]
	v_mfma_f32_16x16x32_bf16 v[42:45], v[142:145], v[190:193], v[42:45]
	v_mfma_f32_16x16x32_bf16 v[30:33], v[130:133], v[194:197], v[30:33]
	v_mfma_f32_16x16x32_bf16 v[30:33], v[134:137], v[198:201], v[30:33]
	v_mfma_f32_16x16x32_bf16 v[26:29], v[138:141], v[194:197], v[26:29]
	v_mfma_f32_16x16x32_bf16 v[26:29], v[142:145], v[198:201], v[26:29]
	v_mfma_f32_16x16x32_bf16 v[14:17], v[130:133], v[212:215], v[14:17]
	v_mfma_f32_16x16x32_bf16 v[14:17], v[134:137], v[216:219], v[14:17]
	v_mfma_f32_16x16x32_bf16 v[10:13], v[138:141], v[212:215], v[10:13]
	v_mfma_f32_16x16x32_bf16 v[10:13], v[142:145], v[216:219], v[10:13]
	s_nop 0
	s_nop 0
	v_mfma_f32_16x16x32_bf16 v[54:57], v[146:149], v[164:167], v[54:57]
	v_mfma_f32_16x16x32_bf16 v[54:57], v[150:153], v[182:185], v[54:57]
	v_mfma_f32_16x16x32_bf16 v[50:53], v[154:157], v[164:167], v[50:53]
	v_mfma_f32_16x16x32_bf16 v[50:53], v[160:163], v[182:185], v[50:53]
	v_mfma_f32_16x16x32_bf16 v[38:41], v[146:149], v[186:189], v[38:41]
	v_mfma_f32_16x16x32_bf16 v[38:41], v[150:153], v[190:193], v[38:41]
	v_mfma_f32_16x16x32_bf16 v[34:37], v[154:157], v[186:189], v[34:37]
	v_mfma_f32_16x16x32_bf16 v[34:37], v[160:163], v[190:193], v[34:37]
	v_mfma_f32_16x16x32_bf16 v[22:25], v[146:149], v[194:197], v[22:25]
	v_mfma_f32_16x16x32_bf16 v[22:25], v[150:153], v[198:201], v[22:25]
	v_mfma_f32_16x16x32_bf16 v[18:21], v[154:157], v[194:197], v[18:21]
	v_mfma_f32_16x16x32_bf16 v[18:21], v[160:163], v[198:201], v[18:21]
	v_mfma_f32_16x16x32_bf16 v[6:9], v[146:149], v[212:215], v[6:9]
	v_mfma_f32_16x16x32_bf16 v[6:9], v[150:153], v[216:219], v[6:9]
	v_mfma_f32_16x16x32_bf16 v[2:5], v[154:157], v[212:215], v[2:5]
	v_mfma_f32_16x16x32_bf16 v[2:5], v[160:163], v[216:219], v[2:5]
	s_nop 0
	s_barrier
	s_add_i32 s51, 0, 0x18000
	s_add_i32 s52, 0, 0x1c000
	v_add_u32_e32 v142, s51, v205
	v_add_u32_e32 v160, s52, v205
	ds_read_b128 v[130:133], v142
	ds_read_b128 v[134:137], v142 offset:1024
	ds_read_b128 v[138:141], v142 offset:2048
	ds_read_b128 v[142:145], v142 offset:3072
	ds_read_b128 v[146:149], v160
	ds_read_b128 v[150:153], v160 offset:1024
	ds_read_b128 v[154:157], v160 offset:2048
	ds_read_b128 v[160:163], v160 offset:3072
	s_add_u32 s48, s48, 0x100000
	s_addc_u32 s49, s49, 0
	s_mov_b32 m0, s7
	v_lshl_add_u64 v[228:229], s[48:49], 0, v[172:173]
	ds_read_b128 v[164:167], v208 offset:32768
	ds_read_b128 v[182:185], v208 offset:33792
	ds_read_b128 v[186:189], v208 offset:34816
	ds_read_b128 v[190:193], v208 offset:35840
	ds_read_b128 v[194:197], v208 offset:36864
	ds_read_b128 v[198:201], v208 offset:37888
	ds_read_b128 v[212:215], v208 offset:38912
	ds_read_b128 v[216:219], v208 offset:39936
	global_load_lds_dwordx4 v[228:229], off
	v_lshl_add_u64 v[228:229], s[48:49], 0, v[168:169]
	s_mov_b32 m0, s8
	s_nop 0
	global_load_lds_dwordx4 v[228:229], off
	s_waitcnt vmcnt(8)
	s_waitcnt lgkmcnt(0)
	s_barrier
	s_nop 0
	s_waitcnt lgkmcnt(0)
	v_mfma_f32_16x16x32_bf16 v[126:129], v[130:133], v[164:167], v[126:129]
	v_mfma_f32_16x16x32_bf16 v[126:129], v[134:137], v[182:185], v[126:129]
	v_mfma_f32_16x16x32_bf16 v[122:125], v[138:141], v[164:167], v[122:125]
	v_mfma_f32_16x16x32_bf16 v[122:125], v[142:145], v[182:185], v[122:125]
	v_mfma_f32_16x16x32_bf16 v[110:113], v[130:133], v[186:189], v[110:113]
	v_mfma_f32_16x16x32_bf16 v[110:113], v[134:137], v[190:193], v[110:113]
	v_mfma_f32_16x16x32_bf16 v[106:109], v[138:141], v[186:189], v[106:109]
	v_mfma_f32_16x16x32_bf16 v[106:109], v[142:145], v[190:193], v[106:109]
	v_mfma_f32_16x16x32_bf16 v[94:97], v[130:133], v[194:197], v[94:97]
	v_mfma_f32_16x16x32_bf16 v[94:97], v[134:137], v[198:201], v[94:97]
	v_mfma_f32_16x16x32_bf16 v[90:93], v[138:141], v[194:197], v[90:93]
	v_mfma_f32_16x16x32_bf16 v[90:93], v[142:145], v[198:201], v[90:93]
	v_mfma_f32_16x16x32_bf16 v[78:81], v[130:133], v[212:215], v[78:81]
	v_mfma_f32_16x16x32_bf16 v[78:81], v[134:137], v[216:219], v[78:81]
	v_mfma_f32_16x16x32_bf16 v[74:77], v[138:141], v[212:215], v[74:77]
	v_mfma_f32_16x16x32_bf16 v[74:77], v[142:145], v[216:219], v[74:77]
	s_nop 0
	s_nop 0
	v_mfma_f32_16x16x32_bf16 v[118:121], v[146:149], v[164:167], v[118:121]
	v_mfma_f32_16x16x32_bf16 v[118:121], v[150:153], v[182:185], v[118:121]
	v_mfma_f32_16x16x32_bf16 v[114:117], v[154:157], v[164:167], v[114:117]
	v_mfma_f32_16x16x32_bf16 v[114:117], v[160:163], v[182:185], v[114:117]
	v_mfma_f32_16x16x32_bf16 v[102:105], v[146:149], v[186:189], v[102:105]
	v_mfma_f32_16x16x32_bf16 v[102:105], v[150:153], v[190:193], v[102:105]
	v_mfma_f32_16x16x32_bf16 v[98:101], v[154:157], v[186:189], v[98:101]
	v_mfma_f32_16x16x32_bf16 v[98:101], v[160:163], v[190:193], v[98:101]
	v_mfma_f32_16x16x32_bf16 v[86:89], v[146:149], v[194:197], v[86:89]
	v_mfma_f32_16x16x32_bf16 v[86:89], v[150:153], v[198:201], v[86:89]
	v_mfma_f32_16x16x32_bf16 v[82:85], v[154:157], v[194:197], v[82:85]
	v_mfma_f32_16x16x32_bf16 v[82:85], v[160:163], v[198:201], v[82:85]
	v_mfma_f32_16x16x32_bf16 v[70:73], v[146:149], v[212:215], v[70:73]
	v_mfma_f32_16x16x32_bf16 v[70:73], v[150:153], v[216:219], v[70:73]
	v_mfma_f32_16x16x32_bf16 v[66:69], v[154:157], v[212:215], v[66:69]
	v_mfma_f32_16x16x32_bf16 v[66:69], v[160:163], v[216:219], v[66:69]
	s_nop 0
	s_barrier
; #define PG8_STAGE(bufoff, gbase, voff) do { _Pragma("unroll") for (int _i = 0; _i < 2; ++_i) \
;         __builtin_amdgcn_global_load_lds((const unsigned*)((const char*)(gbase) + (voff)[_i]), (PG8_LAS unsigned*)(lds + (bufoff) + ldsw + _i * 8192), 16, 0, 0); } while (0)
; #define PG8_LDA(dst, b, h) do { _Pragma("unroll") for (int m = 0; m < 4; ++m) _Pragma("unroll") for (int k = 0; k < 2; ++k) dst[m][k] = *(const PG8_LAS bf16x8*)(lds + PG8_SA(b, h) + aoff + m * 2048 + k * 1024); } while (0)
; #define PG8_BAR __builtin_amdgcn_s_barrier()
; template <class Epi, class Sched, bool ALIGN_EPI = false, bool SP2 = false>
; __device__ __forceinline__ void gemm_phase(PG8_LAS unsigned char* lds, const Gemm g, const Sched& S, const Epi& E, const int wave_s) {
;     ...
;             PG8_LDA(At, 1, 1); PG8_STAGE(PG8_SB(1, 0), b3, voffB); PG8_STAGE(PG8_SB(1, 1), b3 + bhstep, voffB); PG8_STAGE(PG8_SA(1, 0), a3, voffA);
;             PG8_WAIT_V(8); PG8_WAIT_L(0); PG8_BAR; PG8_MMA(1, 0, At, B0); PG8_MMA(1, 1, At, B1); PG8_BAR; PG8_SCHED;
;             } else {
;             PG8_LDB(B0, 0, 0); PG8_SCHED; PG8_LDA(At, 0, 0); PG8_STAGE(PG8_SA(1, 1), a1 + hstep, voffA);
;             PG8_WAIT_L(8); PG8_BAR; PG8_WAIT_L(0); PG8_MMA(0, 0, At, B0); PG8_BAR; PG8_SCHED;
;             PG8_LDB(B1, 0, 1); PG8_STAGE(PG8_SB(0, 0), b2, voffB);
;             PG8_BAR; PG8_WAIT_L(0); PG8_MMA(0, 1, At, B1); PG8_BAR;
;             PG8_LDA(At, 0, 1); PG8_STAGE(PG8_SA(0, 0), a2, voffA);
;             PG8_BAR; PG8_WAIT_L(0); PG8_MMA(1, 0, At, B0); PG8_BAR; PG8_SCHED;
;             PG8_STAGE(PG8_SB(0, 1), b2 + bhstep, voffB);
;             PG8_WAIT_V(6); PG8_BAR; PG8_MMA(1, 1, At, B1); PG8_BAR;
;             PG8_LDB(B0, 1, 0); PG8_SCHED; PG8_LDA(At, 1, 0); PG8_STAGE(PG8_SA(0, 1), a2 + hstep, voffA);
;             PG8_WAIT_L(8); PG8_BAR; PG8_WAIT_L(0); PG8_MMA(0, 0, At, B0); PG8_BAR; PG8_SCHED;
;             PG8_LDB(B1, 1, 1); PG8_STAGE(PG8_SB(1, 0), b3, voffB);
;             PG8_BAR; PG8_WAIT_L(0); PG8_MMA(0, 1, At, B1); PG8_BAR;
;             PG8_LDA(At, 1, 1); PG8_STAGE(PG8_SA(1, 0), a3, voffA);
;             PG8_BAR; PG8_WAIT_L(0); PG8_MMA(1, 0, At, B0); PG8_BAR; PG8_SCHED;
;             PG8_STAGE(PG8_SB(1, 1), b3 + bhstep, voffB);
;             PG8_WAIT_V(6); PG8_BAR; PG8_MMA(1, 1, At, B1); PG8_BAR;
;             }
;         }
;         if constexpr (ALIGN_EPI) { if (wr == 0) PG8_BAR; }
	s_add_i32 s48, s51, s4
	v_lshl_add_u64 v[220:221], v[220:221], 0, s[24:25]
	s_mov_b32 m0, s48
	ds_read_b128 v[164:167], v208 offset:49152
	ds_read_b128 v[182:185], v208 offset:50176
	ds_read_b128 v[186:189], v208 offset:51200
	ds_read_b128 v[190:193], v208 offset:52224
	ds_read_b128 v[194:197], v208 offset:53248
	ds_read_b128 v[198:201], v208 offset:54272
	ds_read_b128 v[212:215], v208 offset:55296
	ds_read_b128 v[216:219], v208 offset:56320
	global_load_lds_dwordx4 v[220:221], off
	s_add_i32 m0, s48, 0x2000
	s_add_u32 s46, s46, 0x40080
	v_lshl_add_u64 v[220:221], v[222:223], 0, s[24:25]
	s_addc_u32 s47, s47, 0
	s_add_i32 s48, s52, s4
	global_load_lds_dwordx4 v[220:221], off
	v_lshl_add_u64 v[220:221], s[46:47], 0, v[170:171]
	s_mov_b32 m0, s48
	s_nop 0
	global_load_lds_dwordx4 v[220:221], off
	v_lshl_add_u64 v[220:221], s[46:47], 0, v[158:159]
	s_add_i32 m0, s48, 0x2000
	s_nop 0
	global_load_lds_dwordx4 v[220:221], off
	v_lshl_add_u64 v[220:221], v[224:225], 0, s[24:25]
	s_mov_b32 m0, s11
	s_nop 0
	global_load_lds_dwordx4 v[220:221], off
	v_lshl_add_u64 v[220:221], v[226:227], 0, s[24:25]
	s_mov_b32 m0, s12
	s_nop 0
	global_load_lds_dwordx4 v[220:221], off
	s_waitcnt vmcnt(8)
	s_waitcnt lgkmcnt(0)
	s_barrier
	s_nop 0
	s_waitcnt lgkmcnt(0)
	v_mfma_f32_16x16x32_bf16 v[62:65], v[130:133], v[164:167], v[62:65]
	v_mfma_f32_16x16x32_bf16 v[62:65], v[134:137], v[182:185], v[62:65]
	v_mfma_f32_16x16x32_bf16 v[58:61], v[138:141], v[164:167], v[58:61]
	v_mfma_f32_16x16x32_bf16 v[58:61], v[142:145], v[182:185], v[58:61]
	v_mfma_f32_16x16x32_bf16 v[46:49], v[130:133], v[186:189], v[46:49]
	v_mfma_f32_16x16x32_bf16 v[46:49], v[134:137], v[190:193], v[46:49]
	v_mfma_f32_16x16x32_bf16 v[42:45], v[138:141], v[186:189], v[42:45]
	v_mfma_f32_16x16x32_bf16 v[42:45], v[142:145], v[190:193], v[42:45]
	v_mfma_f32_16x16x32_bf16 v[30:33], v[130:133], v[194:197], v[30:33]
	v_mfma_f32_16x16x32_bf16 v[30:33], v[134:137], v[198:201], v[30:33]
	v_mfma_f32_16x16x32_bf16 v[26:29], v[138:141], v[194:197], v[26:29]
	v_mfma_f32_16x16x32_bf16 v[26:29], v[142:145], v[198:201], v[26:29]
	v_mfma_f32_16x16x32_bf16 v[14:17], v[130:133], v[212:215], v[14:17]
	v_mfma_f32_16x16x32_bf16 v[14:17], v[134:137], v[216:219], v[14:17]
	v_mfma_f32_16x16x32_bf16 v[10:13], v[138:141], v[212:215], v[10:13]
	v_mfma_f32_16x16x32_bf16 v[10:13], v[142:145], v[216:219], v[10:13]
	s_nop 0
	s_nop 0
	v_mfma_f32_16x16x32_bf16 v[54:57], v[146:149], v[164:167], v[54:57]
	v_mfma_f32_16x16x32_bf16 v[54:57], v[150:153], v[182:185], v[54:57]
	v_mfma_f32_16x16x32_bf16 v[50:53], v[154:157], v[164:167], v[50:53]
	v_mfma_f32_16x16x32_bf16 v[50:53], v[160:163], v[182:185], v[50:53]
	v_mfma_f32_16x16x32_bf16 v[38:41], v[146:149], v[186:189], v[38:41]
	v_mfma_f32_16x16x32_bf16 v[38:41], v[150:153], v[190:193], v[38:41]
	v_mfma_f32_16x16x32_bf16 v[34:37], v[154:157], v[186:189], v[34:37]
	v_mfma_f32_16x16x32_bf16 v[34:37], v[160:163], v[190:193], v[34:37]
	v_mfma_f32_16x16x32_bf16 v[22:25], v[146:149], v[194:197], v[22:25]
	v_mfma_f32_16x16x32_bf16 v[22:25], v[150:153], v[198:201], v[22:25]
	v_mfma_f32_16x16x32_bf16 v[18:21], v[154:157], v[194:197], v[18:21]
	v_mfma_f32_16x16x32_bf16 v[18:21], v[160:163], v[198:201], v[18:21]
	v_mfma_f32_16x16x32_bf16 v[6:9], v[146:149], v[212:215], v[6:9]
	v_mfma_f32_16x16x32_bf16 v[6:9], v[150:153], v[216:219], v[6:9]
	v_mfma_f32_16x16x32_bf16 v[2:5], v[154:157], v[212:215], v[2:5]
	v_mfma_f32_16x16x32_bf16 v[2:5], v[160:163], v[216:219], v[2:5]
	s_nop 0
	s_barrier
	s_add_i32 s50, s50, 2
	s_add_u32 s42, s42, 0x100
	s_addc_u32 s43, s43, 0
	s_add_u32 s29, s29, 0x100
	s_addc_u32 s45, s45, 0
	s_cmp_gt_u32 s50, 61
	s_cbranch_scc0 .LBB0_923
	s_and_b64 vcc, exec, s[20:21]
	s_cbranch_vccz .LBB0_926
	s_barrier
